# nt hint extended: P0/P5/P7 dwordx4 global loads and the P2-P4 LDS-DMA loads
# baseline (speedup 1.0000x reference)
.LBB0_70:
	v_lshl_add_u64 v[52:53], s[8:9], 0, v[6:7]
	v_lshl_add_u64 v[54:55], s[14:15], 0, v[6:7]
	global_load_dwordx4 v[16:19], v[8:9], off nt
	global_load_dwordx4 v[20:23], v[52:53], off nt
	global_load_dwordx4 v[24:27], v[54:55], off nt
	global_load_dwordx4 v[28:31], v[52:53], off offset:1024 nt
	global_load_dwordx4 v[32:35], v[54:55], off offset:1024 nt
	global_load_dwordx4 v[36:39], v[52:53], off offset:3072 nt
	global_load_dwordx4 v[40:43], v[52:53], off offset:2048 nt
	global_load_dwordx4 v[44:47], v[54:55], off offset:3072 nt
	global_load_dwordx4 v[48:51], v[54:55], off offset:2048 nt
	s_add_i32 s4, s30, 0x8000
	s_ashr_i32 s5, s4, 31
	s_lshl_b64 s[4:5], s[4:5], 11
	v_lshl_add_u64 v[52:53], v[4:5], 0, s[4:5]
	s_add_i32 s30, s30, s6
	s_add_u32 s8, s8, s10
	s_addc_u32 s9, s9, s11
	s_add_u32 s14, s14, s10
	s_addc_u32 s15, s15, s11
	s_cmpk_gt_i32 s30, 0x7fff
	s_waitcnt vmcnt(7)
	v_pk_mul_f32 v[54:55], v[22:23], v[22:23]
	v_pk_mul_f32 v[56:57], v[20:21], v[20:21]
	s_waitcnt vmcnt(6)
	v_pk_mul_f32 v[58:59], v[26:27], v[26:27]
	v_pk_mul_f32 v[60:61], v[24:25], v[24:25]
	s_waitcnt vmcnt(5)
	v_pk_mul_f32 v[62:63], v[30:31], v[30:31]
	v_pk_mul_f32 v[64:65], v[28:29], v[28:29]
	s_waitcnt vmcnt(4)
	v_pk_mul_f32 v[66:67], v[34:35], v[34:35]
	v_pk_mul_f32 v[68:69], v[32:33], v[32:33]
	v_pk_mov_b32 v[78:79], v[56:57], v[54:55] op_sel:[1,0]
	v_mov_b32_e32 v57, v55
	v_pk_mov_b32 v[54:55], v[60:61], v[58:59] op_sel:[1,0]
	v_mov_b32_e32 v61, v59
	v_pk_mov_b32 v[58:59], v[64:65], v[62:63] op_sel:[1,0]
	v_mov_b32_e32 v65, v63
	v_pk_mov_b32 v[62:63], v[68:69], v[66:67] op_sel:[1,0]
	v_mov_b32_e32 v69, v67
	s_waitcnt vmcnt(3)
	v_mul_f32_e32 v77, v36, v36
	s_waitcnt vmcnt(2)
	v_mul_f32_e32 v70, v41, v41
	v_mul_f32_e32 v72, v43, v43
	s_waitcnt vmcnt(0)
	v_mul_f32_e32 v74, v49, v49
	v_mul_f32_e32 v76, v51, v51
	v_pk_add_f32 v[56:57], v[78:79], v[56:57]
	v_pk_add_f32 v[54:55], v[54:55], v[60:61]
	v_pk_add_f32 v[58:59], v[58:59], v[64:65]
	v_pk_add_f32 v[60:61], v[62:63], v[68:69]
	v_mul_f32_e32 v80, v37, v37
	v_mul_f32_e32 v81, v38, v38
	v_mul_f32_e32 v82, v39, v39
	v_mul_f32_e32 v83, v44, v44
	v_mul_f32_e32 v84, v45, v45
	v_mul_f32_e32 v85, v46, v46
	v_mul_f32_e32 v86, v47, v47
	v_pk_fma_f32 v[66:67], v[40:41], v[40:41], v[70:71] op_sel_hi:[1,1,0]
	v_pk_fma_f32 v[70:71], v[42:43], v[42:43], v[72:73] op_sel_hi:[1,1,0]
	v_pk_fma_f32 v[72:73], v[48:49], v[48:49], v[74:75] op_sel_hi:[1,1,0]
	v_pk_fma_f32 v[74:75], v[50:51], v[50:51], v[76:77] op_sel_hi:[1,1,0]
	v_pk_add_f32 v[56:57], v[56:57], v[56:57] op_sel:[0,1] op_sel_hi:[1,0]
	v_pk_add_f32 v[58:59], v[58:59], v[58:59] op_sel:[0,1] op_sel_hi:[1,0]
	v_pk_add_f32 v[54:55], v[54:55], v[54:55] op_sel:[0,1] op_sel_hi:[1,0]
	v_pk_add_f32 v[60:61], v[60:61], v[60:61] op_sel:[0,1] op_sel_hi:[1,0]
	v_mov_b32_e32 v67, v81
	v_mov_b32_e32 v71, v82
	v_mov_b32_e32 v73, v85
	v_mov_b32_e32 v75, v86
	v_mov_b32_e32 v57, v77
	v_mov_b32_e32 v59, v80
	v_mov_b32_e32 v55, v83
	v_mov_b32_e32 v61, v84
	v_pk_add_f32 v[62:63], v[66:67], v[70:71]
	v_pk_add_f32 v[64:65], v[72:73], v[74:75]
	v_pk_add_f32 v[56:57], v[56:57], v[58:59]
	v_pk_add_f32 v[54:55], v[54:55], v[60:61]
	v_pk_add_f32 v[56:57], v[56:57], v[62:63]
	v_pk_add_f32 v[54:55], v[54:55], v[64:65]
	v_mov_b32_e32 v59, v56
	v_mov_b32_e32 v58, v54
	v_mov_b32_e32 v56, v55
	v_pk_add_f32 v[54:55], v[58:59], v[56:57]
	ds_bpermute_b32 v57, v1, v55
	ds_bpermute_b32 v56, v1, v54
	s_waitcnt lgkmcnt(0)
	v_pk_add_f32 v[54:55], v[54:55], v[56:57]
	ds_bpermute_b32 v57, v11, v55
	ds_bpermute_b32 v56, v11, v54
	s_waitcnt lgkmcnt(0)
	v_pk_add_f32 v[54:55], v[54:55], v[56:57]
	ds_bpermute_b32 v57, v12, v55
	ds_bpermute_b32 v56, v12, v54
	s_waitcnt lgkmcnt(0)
	v_pk_add_f32 v[54:55], v[54:55], v[56:57]
	ds_bpermute_b32 v57, v13, v55
	ds_bpermute_b32 v56, v13, v54
	s_waitcnt lgkmcnt(0)
	v_pk_add_f32 v[54:55], v[54:55], v[56:57]
	ds_bpermute_b32 v57, v14, v55
	ds_bpermute_b32 v56, v14, v54
	s_waitcnt lgkmcnt(0)
	v_pk_add_f32 v[54:55], v[54:55], v[56:57]
	ds_bpermute_b32 v57, v15, v55
	ds_bpermute_b32 v56, v15, v54
	s_waitcnt lgkmcnt(0)
	v_pk_add_f32 v[54:55], v[54:55], v[56:57]
	s_nop 0
	v_pk_fma_f32 v[54:55], v[54:55], s[16:17], v[10:11] op_sel_hi:[1,0,0]
	s_nop 0
	v_mul_f32_e32 v56, 0x4b800000, v55
	v_cmp_gt_f32_e64 s[4:5], s7, v55
	v_mul_f32_e32 v57, 0x4b800000, v54
	v_cmp_gt_f32_e32 vcc, s7, v54
	v_cndmask_b32_e64 v55, v55, v56, s[4:5]
	v_rsq_f32_e32 v55, v55
	v_cndmask_b32_e32 v54, v54, v57, vcc
	v_rsq_f32_e32 v56, v54
	v_mul_f32_e32 v54, 0x45800000, v55
	v_cndmask_b32_e64 v54, v55, v54, s[4:5]
	v_mul_f32_e32 v57, 0x45800000, v56
	v_cndmask_b32_e32 v56, v56, v57, vcc
	v_pk_mul_f32 v[20:21], v[54:55], v[20:21] op_sel_hi:[0,1]
	v_pk_mul_f32 v[22:23], v[54:55], v[22:23] op_sel_hi:[0,1]
	v_pk_mul_f32 v[24:25], v[56:57], v[24:25] op_sel_hi:[0,1]
	v_pk_mul_f32 v[26:27], v[56:57], v[26:27] op_sel_hi:[0,1]
	v_pk_mul_f32 v[22:23], v[18:19], v[22:23]
	v_pk_mul_f32 v[20:21], v[16:17], v[20:21]
	v_pk_mul_f32 v[18:19], v[18:19], v[26:27]
	v_pk_mul_f32 v[16:17], v[16:17], v[24:25]
	v_cvt_pk_bf16_f32 v20, v20, v21
	v_cvt_pk_bf16_f32 v21, v22, v23
	v_cvt_pk_bf16_f32 v16, v16, v17
	v_cvt_pk_bf16_f32 v17, v18, v19
	global_store_dwordx2 v[2:3], v[20:21], off offset:-1024
	global_store_dwordx2 v[52:53], v[16:17], off
	global_load_dwordx4 v[16:19], v[8:9], off offset:1024 nt
	v_pk_mul_f32 v[20:21], v[54:55], v[28:29] op_sel_hi:[0,1]
	v_pk_mul_f32 v[22:23], v[54:55], v[30:31] op_sel_hi:[0,1]
	v_pk_mul_f32 v[24:25], v[56:57], v[32:33] op_sel_hi:[0,1]
	v_pk_mul_f32 v[26:27], v[56:57], v[34:35] op_sel_hi:[0,1]
	s_waitcnt vmcnt(0)
	v_pk_mul_f32 v[22:23], v[18:19], v[22:23]
	v_pk_mul_f32 v[20:21], v[16:17], v[20:21]
	v_pk_mul_f32 v[18:19], v[18:19], v[26:27]
	v_pk_mul_f32 v[16:17], v[16:17], v[24:25]
	v_cvt_pk_bf16_f32 v20, v20, v21
	v_cvt_pk_bf16_f32 v21, v22, v23
	v_cvt_pk_bf16_f32 v16, v16, v17
	v_cvt_pk_bf16_f32 v17, v18, v19
	global_store_dwordx2 v[2:3], v[20:21], off offset:-512
	global_store_dwordx2 v[52:53], v[16:17], off offset:512
	global_load_dwordx4 v[16:19], v[8:9], off offset:2048 nt
	v_pk_mul_f32 v[20:21], v[54:55], v[40:41] op_sel_hi:[0,1]
	v_pk_mul_f32 v[22:23], v[54:55], v[42:43] op_sel_hi:[0,1]
	v_pk_mul_f32 v[24:25], v[56:57], v[48:49] op_sel_hi:[0,1]
	v_pk_mul_f32 v[26:27], v[56:57], v[50:51] op_sel_hi:[0,1]
	s_waitcnt vmcnt(0)
	v_pk_mul_f32 v[22:23], v[18:19], v[22:23]
	v_pk_mul_f32 v[20:21], v[16:17], v[20:21]
	v_pk_mul_f32 v[18:19], v[18:19], v[26:27]
	v_pk_mul_f32 v[16:17], v[16:17], v[24:25]
	v_cvt_pk_bf16_f32 v20, v20, v21
	v_cvt_pk_bf16_f32 v21, v22, v23
	v_cvt_pk_bf16_f32 v16, v16, v17
	v_cvt_pk_bf16_f32 v17, v18, v19
	global_store_dwordx2 v[2:3], v[20:21], off
	global_store_dwordx2 v[52:53], v[16:17], off offset:1024
	global_load_dwordx4 v[16:19], v[8:9], off offset:3072 nt
	v_pk_mul_f32 v[20:21], v[54:55], v[36:37] op_sel_hi:[0,1]
	v_pk_mul_f32 v[22:23], v[54:55], v[38:39] op_sel_hi:[0,1]
	v_pk_mul_f32 v[24:25], v[56:57], v[44:45] op_sel_hi:[0,1]
	v_pk_mul_f32 v[26:27], v[56:57], v[46:47] op_sel_hi:[0,1]
	s_waitcnt vmcnt(0)
	v_pk_mul_f32 v[22:23], v[18:19], v[22:23]
	v_pk_mul_f32 v[20:21], v[16:17], v[20:21]
	v_pk_mul_f32 v[18:19], v[18:19], v[26:27]
	v_pk_mul_f32 v[16:17], v[16:17], v[24:25]
	v_cvt_pk_bf16_f32 v20, v20, v21
	v_cvt_pk_bf16_f32 v21, v22, v23
	v_cvt_pk_bf16_f32 v16, v16, v17
	v_cvt_pk_bf16_f32 v17, v18, v19
	global_store_dwordx2 v[2:3], v[20:21], off offset:512
	global_store_dwordx2 v[52:53], v[16:17], off offset:1536
	v_lshl_add_u64 v[2:3], v[2:3], 0, s[12:13]
	s_cbranch_scc0 .LBB0_70

.LBB0_534:
	v_bfe_i32 v3, v15, 27, 1
	v_lshlrev_b32_e32 v2, 4, v15
	v_lshrrev_b32_e32 v3, 22, v3
	v_add_u32_e32 v3, v2, v3
	v_and_b32_e32 v3, 0xfffffc00, v3
	v_sub_u32_e32 v3, v2, v3
	v_lshrrev_b32_e32 v4, 4, v3
	v_ashrrev_i32_e32 v0, 31, v15
	v_bitop3_b32 v4, v4, v3, 32 bitop3:0x6c
	v_ashrrev_i32_e32 v3, 31, v3
	v_lshrrev_b32_e32 v0, 26, v0
	v_lshrrev_b32_e32 v3, 26, v3
	v_add_u32_e32 v0, v15, v0
	v_add_u32_e32 v3, v4, v3
	v_ashrrev_i32_e32 v0, 6, v0
	v_ashrrev_i32_e32 v10, 6, v3
	v_lshlrev_b32_e32 v5, 3, v0
	v_mul_i32_i24_e32 v6, 64, v10
	v_and_b32_e32 v5, -16, v5
	v_sub_u32_e32 v4, v4, v6
	v_add_u32_e32 v3, v10, v5
	v_lshlrev_b32_e32 v5, 5, v0
	v_ashrrev_i16_sdwa v4, v161, sext(v4) dst_sel:DWORD dst_unused:UNUSED_PAD src0_sel:DWORD src1_sel:BYTE_0
	v_and_b32_e32 v5, 32, v5
	v_bfe_i32 v11, v4, 0, 16
	v_and_b32_e32 v7, 3, v10
	s_mov_b32 s3, 0x1fffe0
	v_add_lshl_u32 v5, v5, v11, 1
	v_add_u32_e32 v2, 0x2000, v2
	v_lshlrev_b32_e32 v4, 1, v3
	v_lshrrev_b32_e32 v6, 2, v3
	v_and_or_b32 v7, v3, s3, v7
	v_lshl_add_u32 v136, v3, 11, v5
	v_ashrrev_i32_e32 v3, 31, v2
	v_lshrrev_b32_e32 v3, 22, v3
	v_add_u32_e32 v3, v2, v3
	v_ashrrev_i32_e32 v12, 10, v3
	v_mul_i32_i24_e32 v3, 0x400, v12
	v_sub_u32_e32 v2, v2, v3
	v_and_b32_e32 v4, 24, v4
	v_and_b32_e32 v6, 4, v6
	v_lshrrev_b32_e32 v3, 4, v2
	v_or3_b32 v4, v7, v6, v4
	v_bitop3_b32 v2, v3, v2, 32 bitop3:0x6c
	v_lshl_add_u32 v138, v4, 11, v5
	v_ashrrev_i32_e32 v4, 31, v2
	v_lshrrev_b32_e32 v4, 26, v4
	v_lshlrev_b32_e32 v3, 3, v12
	v_add_u32_e32 v4, v2, v4
	v_and_b32_e32 v3, -16, v3
	v_ashrrev_i32_e32 v13, 6, v4
	v_add_u32_e32 v3, v13, v3
	v_and_b32_e32 v6, 3, v13
	s_add_i32 s2, s8, s2
	v_and_or_b32 v6, v3, s3, v6
	s_ashr_i32 s3, s2, 31
	s_lshr_b32 s3, s3, 27
	s_add_i32 s3, s2, s3
	s_ashr_i32 s8, s3, 5
	s_and_b32 s3, s3, 0xffe0
	s_sub_i32 s2, s2, s3
	s_bfe_i32 s3, s2, 0x80000
	s_bfe_u32 s3, s3, 0x3000c
	s_add_i32 s3, s2, s3
	s_lshl_b32 s10, s8, 3
	s_bfe_i32 s8, s3, 0x80000
	s_and_b32 s3, s3, 0xf8
	s_sub_i32 s2, s2, s3
	s_sext_i32_i16 s8, s8
	s_sext_i32_i8 s2, s2
	s_lshr_b32 s8, s8, 3
	s_add_i32 s12, s10, s2
	v_and_b32_e32 v4, 0xc0, v4
	s_ashr_i32 s15, s9, 6
	s_ashr_i32 s13, s12, 31
	s_bfe_i64 s[10:11], s[8:9], 0x100000
	s_ashr_i32 s14, s9, 8
	v_sub_u32_e32 v2, v2, v4
	s_lshl_b32 s57, s15, 10
	s_lshl_b64 s[2:3], s[12:13], 19
	s_lshl_b64 s[10:11], s[10:11], 19
	v_ashrrev_i16_sdwa v2, v161, sext(v2) dst_sel:DWORD dst_unused:UNUSED_PAD src0_sel:DWORD src1_sel:BYTE_0
	s_add_u32 s10, s0, s10
	v_lshlrev_b32_e32 v5, 5, v12
	v_bfe_i32 v14, v2, 0, 16
	v_lshlrev_b32_e32 v2, 1, v3
	v_lshrrev_b32_e32 v4, 2, v3
	s_addc_u32 s11, s1, s11
	s_add_i32 s58, s57, 0
	v_and_b32_e32 v5, 32, v5
	v_and_b32_e32 v2, 24, v2
	v_and_b32_e32 v4, 4, v4
	s_add_i32 m0, s58, 0x10000
	v_or3_b32 v2, v6, v4, v2
	v_add_lshl_u32 v4, v5, v14, 1
	global_load_lds_dwordx4 v138, s[10:11] nt
	s_add_i32 m0, s58, 0x12000
	v_lshl_add_u32 v142, v2, 11, v4
	s_add_u32 s24, s10, 0x40000
	global_load_lds_dwordx4 v142, s[10:11] nt
	s_addc_u32 s25, s11, 0
	s_add_i32 m0, s58, 0x14000
	v_lshl_add_u32 v140, v3, 11, v4
	global_load_lds_dwordx4 v138, s[24:25] nt
	s_add_i32 m0, s58, 0x16000
	s_add_u32 s52, s74, s2
	s_addc_u32 s53, s75, s3
	s_add_i32 s59, s58, 0x2000
	global_load_lds_dwordx4 v142, s[24:25] nt
	s_mov_b32 m0, s58
	s_add_u32 s2, s52, 0x40000
	global_load_lds_dwordx4 v136, s[52:53] nt
	s_mov_b32 m0, s59
	s_addc_u32 s3, s53, 0
	s_add_i32 s60, s58, 0x4000
	global_load_lds_dwordx4 v140, s[52:53] nt
	s_mov_b32 m0, s60
	s_add_i32 s61, s58, 0x6000
	global_load_lds_dwordx4 v136, s[2:3] nt
	s_mov_b32 m0, s61
	v_mov_b32_e32 v139, v1
	global_load_lds_dwordx4 v140, s[2:3] nt
	v_mov_b32_e32 v143, v1
	v_mov_b32_e32 v137, v1
	v_mov_b32_e32 v141, v1
	s_cmp_eq_u32 s14, 1
	v_lshl_add_u64 v[8:9], s[10:11], 0, v[138:139]
	v_lshl_add_u64 v[6:7], s[10:11], 0, v[142:143]
	v_lshl_add_u64 v[2:3], s[52:53], 0, v[136:137]
	s_cselect_b64 s[2:3], -1, 0
	s_cmp_lg_u32 s14, 1
	v_lshl_add_u64 v[4:5], s[52:53], 0, v[140:141]
	s_cbranch_scc1 .LBB0_536
	s_barrier
.LBB0_536:
	s_sext_i32_i8 s13, s8
	s_lshl_b64 s[24:25], s[88:89], 1
	v_readlane_b32 s8, v254, 16
	v_bfe_u32 v158, v15, 4, 2
	s_add_u32 s42, s8, s24
	v_readlane_b32 s8, v254, 17
	v_and_b32_e32 v147, 15, v15
	v_lshlrev_b32_e32 v16, 4, v158
	v_lshlrev_b32_e32 v15, 2, v15
	s_addc_u32 s43, s8, s25
	v_lshl_or_b32 v16, v147, 6, v16
	s_lshl_b32 s8, s14, 13
	v_and_b32_e32 v15, 32, v15
	v_bitop3_b32 v17, v16, s8, v15 bitop3:0xde
	s_lshl_b32 s8, s15, 5
	s_and_b32 s63, s8, 0x60
	s_add_i32 m0, s58, 0x18000
	v_lshl_add_u64 v[8:9], v[8:9], 0, s[90:91]
	s_lshl_b32 s62, s14, 6
	s_lshl_b32 s8, s63, 7
	s_waitcnt vmcnt(2)
	s_barrier
	global_load_lds_dwordx4 v[8:9], off nt
	v_lshl_add_u64 v[6:7], v[6:7], 0, s[90:91]
	s_add_i32 m0, s58, 0x1a000
	s_add_i32 s64, s58, 0x8000
	s_add_i32 s65, s58, 0xa000
	global_load_lds_dwordx4 v[6:7], off nt
	v_lshl_add_u64 v[2:3], v[2:3], 0, s[90:91]
	s_mov_b32 m0, s64
	s_add_u32 s14, s10, 0x40080
	global_load_lds_dwordx4 v[2:3], off nt
	v_lshl_add_u64 v[2:3], v[4:5], 0, s[90:91]
	s_mov_b32 m0, s65
	s_addc_u32 s15, s11, 0
	global_load_lds_dwordx4 v[2:3], off nt
	s_add_i32 m0, s58, 0x1c000
	v_lshl_add_u64 v[2:3], s[14:15], 0, v[138:139]
	global_load_lds_dwordx4 v[2:3], off nt
	v_lshl_add_u64 v[2:3], s[14:15], 0, v[142:143]
	s_add_i32 m0, s58, 0x1e000
	s_cmpk_lt_u32 s9, 0x100
	global_load_lds_dwordx4 v[2:3], off nt
	v_lshlrev_b32_e32 v2, 14, v0
	v_and_b32_e32 v2, 0xffff8000, v2
	v_lshl_add_u32 v2, v10, 11, v2
	v_and_b32_e32 v0, 1, v0
	v_lshl_or_b32 v0, v0, 6, v2
	v_lshl_add_u32 v144, v11, 1, v0
	v_lshlrev_b32_e32 v0, 14, v12
	v_and_b32_e32 v0, 0xffff8000, v0
	s_waitcnt vmcnt(6)
	v_lshl_add_u32 v0, v13, 11, v0
	v_and_b32_e32 v2, 1, v12
	v_lshl_or_b32 v0, v2, 6, v0
	v_or_b32_e32 v159, s62, v147
	v_bitop3_b32 v160, v16, s8, v15 bitop3:0xde
	s_cselect_b64 s[8:9], -1, 0
	v_lshl_or_b32 v162, v158, 3, s63
	s_ashr_i32 s66, s16, 31
	v_mov_b32_e32 v145, v1
	v_lshl_add_u32 v152, v14, 1, v0
	v_mov_b32_e32 v153, v1
	s_mov_b32 s67, 0
	v_add_u32_e32 v163, 0, v17
	s_barrier
	s_branch .LBB0_539

.LBB0_546:
	s_add_u32 s12, s52, s10
	s_addc_u32 s13, s53, s11
	s_add_u32 s12, s12, 0x100
	s_addc_u32 s13, s13, 0
	s_add_u32 s30, s45, s10
	s_addc_u32 s31, s47, s11
	s_cmpk_eq_i32 s10, 0x700
	s_cselect_b32 s55, s14, s13
	s_cselect_b32 s54, s15, s12
	s_cselect_b32 s13, s26, s31
	s_cselect_b32 s12, s27, s30
	s_add_i32 s30, 0, 0x10000
	v_add_u32_e32 v0, s30, v160
	s_add_i32 s34, 0, 0x14000
	ds_read_b128 v[132:135], v0
	ds_read_b128 v[164:167], v0 offset:1024
	ds_read_b128 v[168:171], v0 offset:2048
	ds_read_b128 v[172:175], v0 offset:3072
	v_add_u32_e32 v0, s34, v160
	ds_read_b128 v[198:201], v0
	ds_read_b128 v[202:205], v0 offset:1024
	ds_read_b128 v[206:209], v0 offset:2048
	ds_read_b128 v[210:213], v0 offset:3072
	v_lshl_add_u64 v[2:3], v[154:155], 0, s[10:11]
	s_add_i32 m0, s58, 0xc000
	ds_read_b128 v[216:219], v163
	ds_read_b128 v[220:223], v163 offset:1024
	ds_read_b128 v[224:227], v163 offset:2048
	ds_read_b128 v[228:231], v163 offset:3072
	ds_read_b128 v[232:235], v163 offset:4096
	ds_read_b128 v[236:239], v163 offset:5120
	ds_read_b128 v[240:243], v163 offset:6144
	ds_read_b128 v[244:247], v163 offset:7168
	global_load_lds_dwordx4 v[2:3], off
	v_lshl_add_u64 v[2:3], v[156:157], 0, s[10:11]
	s_add_i32 m0, s58, 0xe000
	s_nop 0
	global_load_lds_dwordx4 v[2:3], off
	s_waitcnt vmcnt(8)
	s_waitcnt lgkmcnt(0)
	s_barrier
	s_waitcnt lgkmcnt(0)
	v_mfma_f32_16x16x32_bf16 v[128:131], v[132:135], v[216:219], v[128:131]
	v_mfma_f32_16x16x32_bf16 v[124:127], v[168:171], v[216:219], v[124:127]
	v_mfma_f32_16x16x32_bf16 v[112:115], v[132:135], v[224:227], v[112:115]
	v_mfma_f32_16x16x32_bf16 v[108:111], v[168:171], v[224:227], v[108:111]
	v_mfma_f32_16x16x32_bf16 v[96:99], v[132:135], v[232:235], v[96:99]
	v_mfma_f32_16x16x32_bf16 v[92:95], v[168:171], v[232:235], v[92:95]
	v_mfma_f32_16x16x32_bf16 v[80:83], v[132:135], v[240:243], v[80:83]
	v_mfma_f32_16x16x32_bf16 v[76:79], v[168:171], v[240:243], v[76:79]
	v_mfma_f32_16x16x32_bf16 v[128:131], v[164:167], v[220:223], v[128:131]
	v_mfma_f32_16x16x32_bf16 v[124:127], v[172:175], v[220:223], v[124:127]
	v_mfma_f32_16x16x32_bf16 v[112:115], v[164:167], v[228:231], v[112:115]
	v_mfma_f32_16x16x32_bf16 v[108:111], v[172:175], v[228:231], v[108:111]
	v_mfma_f32_16x16x32_bf16 v[96:99], v[164:167], v[236:239], v[96:99]
	v_mfma_f32_16x16x32_bf16 v[92:95], v[172:175], v[236:239], v[92:95]
	v_mfma_f32_16x16x32_bf16 v[80:83], v[164:167], v[244:247], v[80:83]
	v_mfma_f32_16x16x32_bf16 v[76:79], v[172:175], v[244:247], v[76:79]
	v_mfma_f32_16x16x32_bf16 v[120:123], v[198:201], v[216:219], v[120:123]
	v_mfma_f32_16x16x32_bf16 v[116:119], v[206:209], v[216:219], v[116:119]
	v_mfma_f32_16x16x32_bf16 v[104:107], v[198:201], v[224:227], v[104:107]
	v_mfma_f32_16x16x32_bf16 v[100:103], v[206:209], v[224:227], v[100:103]
	v_mfma_f32_16x16x32_bf16 v[88:91], v[198:201], v[232:235], v[88:91]
	v_mfma_f32_16x16x32_bf16 v[84:87], v[206:209], v[232:235], v[84:87]
	v_mfma_f32_16x16x32_bf16 v[72:75], v[198:201], v[240:243], v[72:75]
	v_mfma_f32_16x16x32_bf16 v[68:71], v[206:209], v[240:243], v[68:71]
	v_mfma_f32_16x16x32_bf16 v[120:123], v[202:205], v[220:223], v[120:123]
	v_mfma_f32_16x16x32_bf16 v[116:119], v[210:213], v[220:223], v[116:119]
	v_mfma_f32_16x16x32_bf16 v[104:107], v[202:205], v[228:231], v[104:107]
	v_mfma_f32_16x16x32_bf16 v[100:103], v[210:213], v[228:231], v[100:103]
	v_mfma_f32_16x16x32_bf16 v[88:91], v[202:205], v[236:239], v[88:91]
	v_mfma_f32_16x16x32_bf16 v[84:87], v[210:213], v[236:239], v[84:87]
	v_mfma_f32_16x16x32_bf16 v[72:75], v[202:205], v[244:247], v[72:75]
	v_mfma_f32_16x16x32_bf16 v[68:71], v[210:213], v[244:247], v[68:71]
	s_barrier
	s_add_i32 s30, s30, s57
	v_lshl_add_u64 v[176:177], s[12:13], 0, v[138:139]
	s_mov_b32 m0, s30
	ds_read_b128 v[216:219], v163 offset:16384
	ds_read_b128 v[220:223], v163 offset:17408
	ds_read_b128 v[224:227], v163 offset:18432
	ds_read_b128 v[228:231], v163 offset:19456
	ds_read_b128 v[232:235], v163 offset:20480
	ds_read_b128 v[236:239], v163 offset:21504
	ds_read_b128 v[240:243], v163 offset:22528
	ds_read_b128 v[244:247], v163 offset:23552
	global_load_lds_dwordx4 v[176:177], off
	s_add_i32 m0, s30, 0x2000
	s_add_u32 s30, s12, 0x40000
	v_lshl_add_u64 v[248:249], s[12:13], 0, v[142:143]
	s_addc_u32 s31, s13, 0
	s_add_i32 s34, s34, s57
	global_load_lds_dwordx4 v[248:249], off
	v_lshl_add_u64 v[2:3], s[30:31], 0, v[138:139]
	s_mov_b32 m0, s34
	v_lshl_add_u64 v[250:251], s[54:55], 0, v[136:137]
	global_load_lds_dwordx4 v[2:3], off
	v_lshl_add_u64 v[2:3], s[30:31], 0, v[142:143]
	s_add_i32 m0, s34, 0x2000
	v_lshl_add_u64 v[252:253], s[54:55], 0, v[140:141]
	global_load_lds_dwordx4 v[2:3], off
	s_mov_b32 m0, s58
	s_nop 0
	global_load_lds_dwordx4 v[250:251], off
	s_mov_b32 m0, s59
	s_nop 0
	global_load_lds_dwordx4 v[252:253], off
	s_waitcnt vmcnt(8)
	s_waitcnt lgkmcnt(0)
	s_barrier
	s_waitcnt lgkmcnt(0)
	v_mfma_f32_16x16x32_bf16 v[64:67], v[132:135], v[216:219], v[64:67]
	v_mfma_f32_16x16x32_bf16 v[60:63], v[168:171], v[216:219], v[60:63]
	v_mfma_f32_16x16x32_bf16 v[48:51], v[132:135], v[224:227], v[48:51]
	v_mfma_f32_16x16x32_bf16 v[44:47], v[168:171], v[224:227], v[44:47]
	v_mfma_f32_16x16x32_bf16 v[32:35], v[132:135], v[232:235], v[32:35]
	v_mfma_f32_16x16x32_bf16 v[28:31], v[168:171], v[232:235], v[28:31]
	v_mfma_f32_16x16x32_bf16 v[16:19], v[132:135], v[240:243], v[16:19]
	v_mfma_f32_16x16x32_bf16 v[12:15], v[168:171], v[240:243], v[12:15]
	v_mfma_f32_16x16x32_bf16 v[64:67], v[164:167], v[220:223], v[64:67]
	v_mfma_f32_16x16x32_bf16 v[60:63], v[172:175], v[220:223], v[60:63]
	v_mfma_f32_16x16x32_bf16 v[48:51], v[164:167], v[228:231], v[48:51]
	v_mfma_f32_16x16x32_bf16 v[44:47], v[172:175], v[228:231], v[44:47]
	v_mfma_f32_16x16x32_bf16 v[32:35], v[164:167], v[236:239], v[32:35]
	v_mfma_f32_16x16x32_bf16 v[28:31], v[172:175], v[236:239], v[28:31]
	v_mfma_f32_16x16x32_bf16 v[16:19], v[164:167], v[244:247], v[16:19]
	v_mfma_f32_16x16x32_bf16 v[12:15], v[172:175], v[244:247], v[12:15]
	v_mfma_f32_16x16x32_bf16 v[56:59], v[198:201], v[216:219], v[56:59]
	v_mfma_f32_16x16x32_bf16 v[52:55], v[206:209], v[216:219], v[52:55]
	v_mfma_f32_16x16x32_bf16 v[40:43], v[198:201], v[224:227], v[40:43]
	v_mfma_f32_16x16x32_bf16 v[36:39], v[206:209], v[224:227], v[36:39]
	v_mfma_f32_16x16x32_bf16 v[24:27], v[198:201], v[232:235], v[24:27]
	v_mfma_f32_16x16x32_bf16 v[20:23], v[206:209], v[232:235], v[20:23]
	v_mfma_f32_16x16x32_bf16 v[8:11], v[198:201], v[240:243], v[8:11]
	v_mfma_f32_16x16x32_bf16 v[2:5], v[206:209], v[240:243], v[4:7]
	v_mfma_f32_16x16x32_bf16 v[56:59], v[202:205], v[220:223], v[56:59]
	v_mfma_f32_16x16x32_bf16 v[52:55], v[210:213], v[220:223], v[52:55]
	v_mfma_f32_16x16x32_bf16 v[40:43], v[202:205], v[228:231], v[40:43]
	v_mfma_f32_16x16x32_bf16 v[36:39], v[210:213], v[228:231], v[36:39]
	v_mfma_f32_16x16x32_bf16 v[24:27], v[202:205], v[236:239], v[24:27]
	v_mfma_f32_16x16x32_bf16 v[20:23], v[210:213], v[236:239], v[20:23]
	v_mfma_f32_16x16x32_bf16 v[8:11], v[202:205], v[244:247], v[8:11]
	v_mfma_f32_16x16x32_bf16 v[2:5], v[210:213], v[244:247], v[2:5]
	s_barrier
	s_add_i32 s34, 0, 0x18000
	v_add_u32_e32 v0, s34, v160
	s_add_i32 s35, 0, 0x1c000
	ds_read_b128 v[132:135], v0
	ds_read_b128 v[164:167], v0 offset:1024
	ds_read_b128 v[168:171], v0 offset:2048
	ds_read_b128 v[172:175], v0 offset:3072
	v_add_u32_e32 v0, s35, v160
	ds_read_b128 v[198:201], v0
	ds_read_b128 v[202:205], v0 offset:1024
	ds_read_b128 v[206:209], v0 offset:2048
	ds_read_b128 v[210:213], v0 offset:3072
	s_add_u32 s30, s54, 0x40000
	s_addc_u32 s31, s55, 0
	s_mov_b32 m0, s60
	v_lshl_add_u64 v[6:7], s[30:31], 0, v[136:137]
	ds_read_b128 v[216:219], v163 offset:32768
	ds_read_b128 v[220:223], v163 offset:33792
	ds_read_b128 v[224:227], v163 offset:34816
	ds_read_b128 v[228:231], v163 offset:35840
	ds_read_b128 v[232:235], v163 offset:36864
	ds_read_b128 v[236:239], v163 offset:37888
	ds_read_b128 v[240:243], v163 offset:38912
	ds_read_b128 v[244:247], v163 offset:39936
	global_load_lds_dwordx4 v[6:7], off
	v_lshl_add_u64 v[6:7], s[30:31], 0, v[140:141]
	s_mov_b32 m0, s61
	s_nop 0
	global_load_lds_dwordx4 v[6:7], off
	s_waitcnt vmcnt(8)
	s_waitcnt lgkmcnt(0)
	s_barrier
	s_waitcnt lgkmcnt(0)
	v_mfma_f32_16x16x32_bf16 v[128:131], v[132:135], v[216:219], v[128:131]
	v_mfma_f32_16x16x32_bf16 v[124:127], v[168:171], v[216:219], v[124:127]
	v_mfma_f32_16x16x32_bf16 v[112:115], v[132:135], v[224:227], v[112:115]
	v_mfma_f32_16x16x32_bf16 v[108:111], v[168:171], v[224:227], v[108:111]
	v_mfma_f32_16x16x32_bf16 v[96:99], v[132:135], v[232:235], v[96:99]
	v_mfma_f32_16x16x32_bf16 v[92:95], v[168:171], v[232:235], v[92:95]
	v_mfma_f32_16x16x32_bf16 v[80:83], v[132:135], v[240:243], v[80:83]
	v_mfma_f32_16x16x32_bf16 v[76:79], v[168:171], v[240:243], v[76:79]
	v_mfma_f32_16x16x32_bf16 v[128:131], v[164:167], v[220:223], v[128:131]
	v_mfma_f32_16x16x32_bf16 v[124:127], v[172:175], v[220:223], v[124:127]
	v_mfma_f32_16x16x32_bf16 v[112:115], v[164:167], v[228:231], v[112:115]
	v_mfma_f32_16x16x32_bf16 v[108:111], v[172:175], v[228:231], v[108:111]
	v_mfma_f32_16x16x32_bf16 v[96:99], v[164:167], v[236:239], v[96:99]
	v_mfma_f32_16x16x32_bf16 v[92:95], v[172:175], v[236:239], v[92:95]
	v_mfma_f32_16x16x32_bf16 v[80:83], v[164:167], v[244:247], v[80:83]
	v_mfma_f32_16x16x32_bf16 v[76:79], v[172:175], v[244:247], v[76:79]
	v_mfma_f32_16x16x32_bf16 v[120:123], v[198:201], v[216:219], v[120:123]
	v_mfma_f32_16x16x32_bf16 v[116:119], v[206:209], v[216:219], v[116:119]
	v_mfma_f32_16x16x32_bf16 v[104:107], v[198:201], v[224:227], v[104:107]
	v_mfma_f32_16x16x32_bf16 v[100:103], v[206:209], v[224:227], v[100:103]
	v_mfma_f32_16x16x32_bf16 v[88:91], v[198:201], v[232:235], v[88:91]
	v_mfma_f32_16x16x32_bf16 v[84:87], v[206:209], v[232:235], v[84:87]
	v_mfma_f32_16x16x32_bf16 v[72:75], v[198:201], v[240:243], v[72:75]
	v_mfma_f32_16x16x32_bf16 v[68:71], v[206:209], v[240:243], v[68:71]
	v_mfma_f32_16x16x32_bf16 v[120:123], v[202:205], v[220:223], v[120:123]
	v_mfma_f32_16x16x32_bf16 v[116:119], v[210:213], v[220:223], v[116:119]
	v_mfma_f32_16x16x32_bf16 v[104:107], v[202:205], v[228:231], v[104:107]
	v_mfma_f32_16x16x32_bf16 v[100:103], v[210:213], v[228:231], v[100:103]
	v_mfma_f32_16x16x32_bf16 v[88:91], v[202:205], v[236:239], v[88:91]
	v_mfma_f32_16x16x32_bf16 v[84:87], v[210:213], v[236:239], v[84:87]
	v_mfma_f32_16x16x32_bf16 v[72:75], v[202:205], v[244:247], v[72:75]
	v_mfma_f32_16x16x32_bf16 v[68:71], v[210:213], v[244:247], v[68:71]
	s_barrier
	s_add_i32 s30, s34, s57
	v_lshl_add_u64 v[6:7], v[176:177], 0, s[90:91]
	s_mov_b32 m0, s30
	ds_read_b128 v[216:219], v163 offset:49152
	ds_read_b128 v[220:223], v163 offset:50176
	ds_read_b128 v[224:227], v163 offset:51200
	ds_read_b128 v[228:231], v163 offset:52224
	ds_read_b128 v[232:235], v163 offset:53248
	ds_read_b128 v[236:239], v163 offset:54272
	ds_read_b128 v[240:243], v163 offset:55296
	ds_read_b128 v[244:247], v163 offset:56320
	global_load_lds_dwordx4 v[6:7], off
	s_add_i32 m0, s30, 0x2000
	s_add_u32 s12, s12, 0x40080
	v_lshl_add_u64 v[6:7], v[248:249], 0, s[90:91]
	s_addc_u32 s13, s13, 0
	s_add_i32 s30, s35, s57
	global_load_lds_dwordx4 v[6:7], off
	v_lshl_add_u64 v[6:7], s[12:13], 0, v[138:139]
	s_mov_b32 m0, s30
	s_nop 0
	global_load_lds_dwordx4 v[6:7], off
	v_lshl_add_u64 v[6:7], s[12:13], 0, v[142:143]
	s_add_i32 m0, s30, 0x2000
	s_nop 0
	global_load_lds_dwordx4 v[6:7], off
	v_lshl_add_u64 v[6:7], v[250:251], 0, s[90:91]
	s_mov_b32 m0, s64
	s_nop 0
	global_load_lds_dwordx4 v[6:7], off
	v_lshl_add_u64 v[6:7], v[252:253], 0, s[90:91]
	s_mov_b32 m0, s65
	s_nop 0
	global_load_lds_dwordx4 v[6:7], off
	s_waitcnt vmcnt(8)
	s_waitcnt lgkmcnt(0)
	s_barrier
	s_waitcnt lgkmcnt(0)
	v_mfma_f32_16x16x32_bf16 v[64:67], v[132:135], v[216:219], v[64:67]
	v_mfma_f32_16x16x32_bf16 v[60:63], v[168:171], v[216:219], v[60:63]
	v_mfma_f32_16x16x32_bf16 v[48:51], v[132:135], v[224:227], v[48:51]
	v_mfma_f32_16x16x32_bf16 v[44:47], v[168:171], v[224:227], v[44:47]
	v_mfma_f32_16x16x32_bf16 v[32:35], v[132:135], v[232:235], v[32:35]
	v_mfma_f32_16x16x32_bf16 v[28:31], v[168:171], v[232:235], v[28:31]
	v_mfma_f32_16x16x32_bf16 v[16:19], v[132:135], v[240:243], v[16:19]
	v_mfma_f32_16x16x32_bf16 v[12:15], v[168:171], v[240:243], v[12:15]
	v_mfma_f32_16x16x32_bf16 v[64:67], v[164:167], v[220:223], v[64:67]
	v_mfma_f32_16x16x32_bf16 v[60:63], v[172:175], v[220:223], v[60:63]
	v_mfma_f32_16x16x32_bf16 v[48:51], v[164:167], v[228:231], v[48:51]
	v_mfma_f32_16x16x32_bf16 v[44:47], v[172:175], v[228:231], v[44:47]
	v_mfma_f32_16x16x32_bf16 v[32:35], v[164:167], v[236:239], v[32:35]
	v_mfma_f32_16x16x32_bf16 v[28:31], v[172:175], v[236:239], v[28:31]
	v_mfma_f32_16x16x32_bf16 v[16:19], v[164:167], v[244:247], v[16:19]
	v_mfma_f32_16x16x32_bf16 v[12:15], v[172:175], v[244:247], v[12:15]
	v_mfma_f32_16x16x32_bf16 v[56:59], v[198:201], v[216:219], v[56:59]
	v_mfma_f32_16x16x32_bf16 v[52:55], v[206:209], v[216:219], v[52:55]
	v_mfma_f32_16x16x32_bf16 v[40:43], v[198:201], v[224:227], v[40:43]
	v_mfma_f32_16x16x32_bf16 v[36:39], v[206:209], v[224:227], v[36:39]
	v_mfma_f32_16x16x32_bf16 v[24:27], v[198:201], v[232:235], v[24:27]
	v_mfma_f32_16x16x32_bf16 v[20:23], v[206:209], v[232:235], v[20:23]
	v_mfma_f32_16x16x32_bf16 v[6:9], v[198:201], v[240:243], v[8:11]
	v_mfma_f32_16x16x32_bf16 v[2:5], v[206:209], v[240:243], v[2:5]
	v_mfma_f32_16x16x32_bf16 v[56:59], v[202:205], v[220:223], v[56:59]
	v_mfma_f32_16x16x32_bf16 v[52:55], v[210:213], v[220:223], v[52:55]
	v_mfma_f32_16x16x32_bf16 v[40:43], v[202:205], v[228:231], v[40:43]
	v_mfma_f32_16x16x32_bf16 v[36:39], v[210:213], v[228:231], v[36:39]
	v_mfma_f32_16x16x32_bf16 v[24:27], v[202:205], v[236:239], v[24:27]
	v_mfma_f32_16x16x32_bf16 v[20:23], v[210:213], v[236:239], v[20:23]
	v_mfma_f32_16x16x32_bf16 v[8:11], v[202:205], v[244:247], v[6:9]
	v_mfma_f32_16x16x32_bf16 v[4:7], v[210:213], v[244:247], v[2:5]
	s_cmpk_lg_i32 s10, 0x300
	s_cbranch_scc1 .Lp5_noearly
	s_and_b64 vcc, exec, s[8:9]
	s_cbranch_vccnz .Lp5_noearly
	v_add_u32_e32 v132, s29, v147
	v_lshl_add_u32 v2, v158, 3, s28
	v_ashrrev_i32_e32 v133, 31, v132
	v_ashrrev_i32_e32 v3, 31, v2
	v_lshlrev_b64 v[132:133], 12, v[132:133]
	v_lshlrev_b64 v[2:3], 1, v[2:3]
	v_lshl_add_u64 v[2:3], s[92:93], 0, v[2:3]
	v_lshl_add_u64 v[2:3], v[2:3], 0, v[132:133]
	s_mov_b64 s[12:13], 0x10000
	global_load_dwordx4 v[216:219], v[2:3], off nt
	global_load_dwordx4 v[220:223], v[2:3], off offset:256 nt
	v_lshl_add_u64 v[2:3], v[2:3], 0, s[12:13]
	global_load_dwordx4 v[224:227], v[2:3], off nt
	global_load_dwordx4 v[228:231], v[2:3], off offset:256 nt
	v_lshl_add_u64 v[2:3], v[2:3], 0, s[12:13]
	global_load_dwordx4 v[232:235], v[2:3], off nt
	global_load_dwordx4 v[236:239], v[2:3], off offset:256 nt
	v_lshl_add_u64 v[2:3], v[2:3], 0, s[12:13]
	global_load_dwordx4 v[240:243], v[2:3], off nt
	global_load_dwordx4 v[244:247], v[2:3], off offset:256 nt
	s_mov_b64 s[12:13], 0x50000
	v_lshl_add_u64 v[2:3], v[2:3], 0, s[12:13]
	s_mov_b64 s[12:13], 0x10000
	global_load_dwordx4 v[198:201], v[2:3], off nt
	global_load_dwordx4 v[202:205], v[2:3], off offset:256 nt
	v_lshl_add_u64 v[2:3], v[2:3], 0, s[12:13]
	global_load_dwordx4 v[206:209], v[2:3], off nt
	global_load_dwordx4 v[210:213], v[2:3], off offset:256 nt
	v_lshl_add_u64 v[2:3], v[2:3], 0, s[12:13]
	global_load_dwordx4 v[164:167], v[2:3], off nt
	global_load_dwordx4 v[168:171], v[2:3], off offset:256 nt
	v_lshl_add_u64 v[2:3], v[2:3], 0, s[12:13]
	global_load_dwordx4 v[172:175], v[2:3], off nt
	global_load_dwordx4 v[132:135], v[2:3], off offset:256 nt

.LBB0_547:
	s_cmpk_lg_i32 s10, 0x400
	s_cbranch_scc1 .LBB0_546
	s_and_b64 vcc, exec, s[8:9]
	s_cbranch_vccz .Lp5_hookwait
	v_add_u32_e32 v132, s29, v147
	v_lshl_add_u32 v2, v158, 3, s28
	v_ashrrev_i32_e32 v133, 31, v132
	v_ashrrev_i32_e32 v3, 31, v2
	v_lshlrev_b64 v[132:133], 12, v[132:133]
	v_lshlrev_b64 v[2:3], 1, v[2:3]
	v_lshl_add_u64 v[2:3], s[92:93], 0, v[2:3]
	v_lshl_add_u64 v[2:3], v[2:3], 0, v[132:133]
	s_mov_b64 s[12:13], 0x10000
	global_load_dwordx4 v[216:219], v[2:3], off nt
	global_load_dwordx4 v[220:223], v[2:3], off offset:256 nt
	v_lshl_add_u64 v[2:3], v[2:3], 0, s[12:13]
	global_load_dwordx4 v[224:227], v[2:3], off nt
	global_load_dwordx4 v[228:231], v[2:3], off offset:256 nt
	v_lshl_add_u64 v[2:3], v[2:3], 0, s[12:13]
	global_load_dwordx4 v[232:235], v[2:3], off nt
	global_load_dwordx4 v[236:239], v[2:3], off offset:256 nt
	v_lshl_add_u64 v[2:3], v[2:3], 0, s[12:13]
	global_load_dwordx4 v[240:243], v[2:3], off nt
	global_load_dwordx4 v[244:247], v[2:3], off offset:256 nt
	s_mov_b64 s[12:13], 0x50000
	v_lshl_add_u64 v[2:3], v[2:3], 0, s[12:13]
	s_mov_b64 s[12:13], 0x10000
	global_load_dwordx4 v[198:201], v[2:3], off nt
	global_load_dwordx4 v[202:205], v[2:3], off offset:256 nt
	v_lshl_add_u64 v[2:3], v[2:3], 0, s[12:13]
	global_load_dwordx4 v[206:209], v[2:3], off nt
	global_load_dwordx4 v[210:213], v[2:3], off offset:256 nt
	v_lshl_add_u64 v[2:3], v[2:3], 0, s[12:13]
	global_load_dwordx4 v[164:167], v[2:3], off nt
	global_load_dwordx4 v[168:171], v[2:3], off offset:256 nt
	v_lshl_add_u64 v[2:3], v[2:3], 0, s[12:13]
	global_load_dwordx4 v[172:175], v[2:3], off nt
	global_load_dwordx4 v[132:135], v[2:3], off offset:256 nt

.LBB0_551:
	v_add_u32_e32 v154, s24, v159
	v_or_b32_e32 v2, s25, v162
	v_ashrrev_i32_e32 v155, 31, v154
	v_ashrrev_i32_e32 v3, 31, v2
	v_lshlrev_b64 v[2:3], 1, v[2:3]
	v_lshlrev_b64 v[156:157], 12, v[154:155]
	v_lshlrev_b64 v[154:155], 11, v[154:155]
	v_lshl_add_u64 v[156:157], s[92:93], 0, v[156:157]
	v_lshl_add_u64 v[154:155], s[42:43], 0, v[154:155]
	v_lshl_add_u64 v[156:157], v[156:157], 0, v[2:3]
	v_lshl_add_u64 v[154:155], v[154:155], 0, v[2:3]
	s_mov_b64 s[12:13], 0x10000
	global_load_dwordx4 v[216:219], v[156:157], off offset:2048 nt
	global_load_dwordx4 v[220:223], v[156:157], off offset:2304 nt
	v_lshl_add_u64 v[156:157], v[156:157], 0, s[12:13]
	global_load_dwordx4 v[224:227], v[156:157], off offset:2048 nt
	global_load_dwordx4 v[228:231], v[156:157], off offset:2304 nt
	v_lshl_add_u64 v[156:157], v[156:157], 0, s[12:13]
	global_load_dwordx4 v[232:235], v[156:157], off offset:2048 nt
	global_load_dwordx4 v[236:239], v[156:157], off offset:2304 nt
	v_lshl_add_u64 v[156:157], v[156:157], 0, s[12:13]
	global_load_dwordx4 v[240:243], v[156:157], off offset:2048 nt
	global_load_dwordx4 v[244:247], v[156:157], off offset:2304 nt
	s_mov_b64 s[12:13], 0x50000
	v_lshl_add_u64 v[156:157], v[156:157], 0, s[12:13]
	s_mov_b64 s[12:13], 0x10000
	global_load_dwordx4 v[198:201], v[156:157], off offset:2048 nt
	global_load_dwordx4 v[202:205], v[156:157], off offset:2304 nt
	v_lshl_add_u64 v[156:157], v[156:157], 0, s[12:13]
	global_load_dwordx4 v[206:209], v[156:157], off offset:2048 nt
	global_load_dwordx4 v[210:213], v[156:157], off offset:2304 nt
	v_lshl_add_u64 v[156:157], v[156:157], 0, s[12:13]
	global_load_dwordx4 v[164:167], v[156:157], off offset:2048 nt
	global_load_dwordx4 v[168:171], v[156:157], off offset:2304 nt
	v_lshl_add_u64 v[156:157], v[156:157], 0, s[12:13]
	global_load_dwordx4 v[172:175], v[156:157], off offset:2048 nt
	global_load_dwordx4 v[132:135], v[156:157], off offset:2304 nt
	s_mov_b64 s[12:13], 0x8000
	s_waitcnt vmcnt(15)
	v_lshlrev_b32_e32 v248, 16, v216
	v_and_b32_e32 v249, 0xffff0000, v216
	v_lshlrev_b32_e32 v250, 16, v217
	v_and_b32_e32 v251, 0xffff0000, v217
	v_lshlrev_b32_e32 v252, 16, v218
	v_and_b32_e32 v253, 0xffff0000, v218
	v_lshlrev_b32_e32 v176, 16, v219
	v_and_b32_e32 v177, 0xffff0000, v219
	v_max_f32_e32 v248, 0xda24260, v248
	v_max_f32_e32 v249, 0xda24260, v249
	v_max_f32_e32 v250, 0xda24260, v250
	v_max_f32_e32 v251, 0xda24260, v251
	v_max_f32_e32 v252, 0xda24260, v252
	v_max_f32_e32 v253, 0xda24260, v253
	v_max_f32_e32 v176, 0xda24260, v176
	v_max_f32_e32 v177, 0xda24260, v177
	v_pk_mul_f32 v[128:129], v[128:129], v[248:249]
	v_pk_mul_f32 v[130:131], v[130:131], v[250:251]
	v_pk_mul_f32 v[124:125], v[124:125], v[252:253]
	v_pk_mul_f32 v[126:127], v[126:127], v[176:177]
	v_cvt_pk_bf16_f32 v216, v128, v129
	v_cvt_pk_bf16_f32 v217, v130, v131
	v_cvt_pk_bf16_f32 v218, v124, v125
	v_cvt_pk_bf16_f32 v219, v126, v127
	global_store_dwordx4 v[154:155], v[216:219], off
	s_waitcnt vmcnt(15)
	v_lshlrev_b32_e32 v248, 16, v220
	v_and_b32_e32 v249, 0xffff0000, v220
	v_lshlrev_b32_e32 v250, 16, v221
	v_and_b32_e32 v251, 0xffff0000, v221
	v_lshlrev_b32_e32 v252, 16, v222
	v_and_b32_e32 v253, 0xffff0000, v222
	v_lshlrev_b32_e32 v176, 16, v223
	v_and_b32_e32 v177, 0xffff0000, v223
	v_max_f32_e32 v248, 0xda24260, v248
	v_max_f32_e32 v249, 0xda24260, v249
	v_max_f32_e32 v250, 0xda24260, v250
	v_max_f32_e32 v251, 0xda24260, v251
	v_max_f32_e32 v252, 0xda24260, v252
	v_max_f32_e32 v253, 0xda24260, v253
	v_max_f32_e32 v176, 0xda24260, v176
	v_max_f32_e32 v177, 0xda24260, v177
	v_pk_mul_f32 v[120:121], v[120:121], v[248:249]
	v_pk_mul_f32 v[122:123], v[122:123], v[250:251]
	v_pk_mul_f32 v[116:117], v[116:117], v[252:253]
	v_pk_mul_f32 v[118:119], v[118:119], v[176:177]
	v_cvt_pk_bf16_f32 v220, v120, v121
	v_cvt_pk_bf16_f32 v221, v122, v123
	v_cvt_pk_bf16_f32 v222, v116, v117
	v_cvt_pk_bf16_f32 v223, v118, v119
	global_store_dwordx4 v[154:155], v[220:223], off offset:256
	v_lshl_add_u64 v[154:155], v[154:155], 0, s[12:13]
	s_waitcnt vmcnt(15)
	v_lshlrev_b32_e32 v248, 16, v224
	v_and_b32_e32 v249, 0xffff0000, v224
	v_lshlrev_b32_e32 v250, 16, v225
	v_and_b32_e32 v251, 0xffff0000, v225
	v_lshlrev_b32_e32 v252, 16, v226
	v_and_b32_e32 v253, 0xffff0000, v226
	v_lshlrev_b32_e32 v176, 16, v227
	v_and_b32_e32 v177, 0xffff0000, v227
	v_max_f32_e32 v248, 0xda24260, v248
	v_max_f32_e32 v249, 0xda24260, v249
	v_max_f32_e32 v250, 0xda24260, v250
	v_max_f32_e32 v251, 0xda24260, v251
	v_max_f32_e32 v252, 0xda24260, v252
	v_max_f32_e32 v253, 0xda24260, v253
	v_max_f32_e32 v176, 0xda24260, v176
	v_max_f32_e32 v177, 0xda24260, v177
	v_pk_mul_f32 v[112:113], v[112:113], v[248:249]
	v_pk_mul_f32 v[114:115], v[114:115], v[250:251]
	v_pk_mul_f32 v[108:109], v[108:109], v[252:253]
	v_pk_mul_f32 v[110:111], v[110:111], v[176:177]
	v_cvt_pk_bf16_f32 v224, v112, v113
	v_cvt_pk_bf16_f32 v225, v114, v115
	v_cvt_pk_bf16_f32 v226, v108, v109
	v_cvt_pk_bf16_f32 v227, v110, v111
	global_store_dwordx4 v[154:155], v[224:227], off
	s_waitcnt vmcnt(15)
	v_lshlrev_b32_e32 v248, 16, v228
	v_and_b32_e32 v249, 0xffff0000, v228
	v_lshlrev_b32_e32 v250, 16, v229
	v_and_b32_e32 v251, 0xffff0000, v229
	v_lshlrev_b32_e32 v252, 16, v230
	v_and_b32_e32 v253, 0xffff0000, v230
	v_lshlrev_b32_e32 v176, 16, v231
	v_and_b32_e32 v177, 0xffff0000, v231
	v_max_f32_e32 v248, 0xda24260, v248
	v_max_f32_e32 v249, 0xda24260, v249
	v_max_f32_e32 v250, 0xda24260, v250
	v_max_f32_e32 v251, 0xda24260, v251
	v_max_f32_e32 v252, 0xda24260, v252
	v_max_f32_e32 v253, 0xda24260, v253
	v_max_f32_e32 v176, 0xda24260, v176
	v_max_f32_e32 v177, 0xda24260, v177
	v_pk_mul_f32 v[104:105], v[104:105], v[248:249]
	v_pk_mul_f32 v[106:107], v[106:107], v[250:251]
	v_pk_mul_f32 v[100:101], v[100:101], v[252:253]
	v_pk_mul_f32 v[102:103], v[102:103], v[176:177]
	v_cvt_pk_bf16_f32 v228, v104, v105
	v_cvt_pk_bf16_f32 v229, v106, v107
	v_cvt_pk_bf16_f32 v230, v100, v101
	v_cvt_pk_bf16_f32 v231, v102, v103
	global_store_dwordx4 v[154:155], v[228:231], off offset:256
	v_lshl_add_u64 v[154:155], v[154:155], 0, s[12:13]
	s_waitcnt vmcnt(15)
	v_lshlrev_b32_e32 v248, 16, v232
	v_and_b32_e32 v249, 0xffff0000, v232
	v_lshlrev_b32_e32 v250, 16, v233
	v_and_b32_e32 v251, 0xffff0000, v233
	v_lshlrev_b32_e32 v252, 16, v234
	v_and_b32_e32 v253, 0xffff0000, v234
	v_lshlrev_b32_e32 v176, 16, v235
	v_and_b32_e32 v177, 0xffff0000, v235
	v_max_f32_e32 v248, 0xda24260, v248
	v_max_f32_e32 v249, 0xda24260, v249
	v_max_f32_e32 v250, 0xda24260, v250
	v_max_f32_e32 v251, 0xda24260, v251
	v_max_f32_e32 v252, 0xda24260, v252
	v_max_f32_e32 v253, 0xda24260, v253
	v_max_f32_e32 v176, 0xda24260, v176
	v_max_f32_e32 v177, 0xda24260, v177
	v_pk_mul_f32 v[96:97], v[96:97], v[248:249]
	v_pk_mul_f32 v[98:99], v[98:99], v[250:251]
	v_pk_mul_f32 v[92:93], v[92:93], v[252:253]
	v_pk_mul_f32 v[94:95], v[94:95], v[176:177]
	v_cvt_pk_bf16_f32 v232, v96, v97
	v_cvt_pk_bf16_f32 v233, v98, v99
	v_cvt_pk_bf16_f32 v234, v92, v93
	v_cvt_pk_bf16_f32 v235, v94, v95
	global_store_dwordx4 v[154:155], v[232:235], off
	s_waitcnt vmcnt(15)
	v_lshlrev_b32_e32 v248, 16, v236
	v_and_b32_e32 v249, 0xffff0000, v236
	v_lshlrev_b32_e32 v250, 16, v237
	v_and_b32_e32 v251, 0xffff0000, v237
	v_lshlrev_b32_e32 v252, 16, v238
	v_and_b32_e32 v253, 0xffff0000, v238
	v_lshlrev_b32_e32 v176, 16, v239
	v_and_b32_e32 v177, 0xffff0000, v239
	v_max_f32_e32 v248, 0xda24260, v248
	v_max_f32_e32 v249, 0xda24260, v249
	v_max_f32_e32 v250, 0xda24260, v250
	v_max_f32_e32 v251, 0xda24260, v251
	v_max_f32_e32 v252, 0xda24260, v252
	v_max_f32_e32 v253, 0xda24260, v253
	v_max_f32_e32 v176, 0xda24260, v176
	v_max_f32_e32 v177, 0xda24260, v177
	v_pk_mul_f32 v[88:89], v[88:89], v[248:249]
	v_pk_mul_f32 v[90:91], v[90:91], v[250:251]
	v_pk_mul_f32 v[84:85], v[84:85], v[252:253]
	v_pk_mul_f32 v[86:87], v[86:87], v[176:177]
	v_cvt_pk_bf16_f32 v236, v88, v89
	v_cvt_pk_bf16_f32 v237, v90, v91
	v_cvt_pk_bf16_f32 v238, v84, v85
	v_cvt_pk_bf16_f32 v239, v86, v87
	global_store_dwordx4 v[154:155], v[236:239], off offset:256
	v_lshl_add_u64 v[154:155], v[154:155], 0, s[12:13]
	s_waitcnt vmcnt(15)
	v_lshlrev_b32_e32 v248, 16, v240
	v_and_b32_e32 v249, 0xffff0000, v240
	v_lshlrev_b32_e32 v250, 16, v241
	v_and_b32_e32 v251, 0xffff0000, v241
	v_lshlrev_b32_e32 v252, 16, v242
	v_and_b32_e32 v253, 0xffff0000, v242
	v_lshlrev_b32_e32 v176, 16, v243
	v_and_b32_e32 v177, 0xffff0000, v243
	v_max_f32_e32 v248, 0xda24260, v248
	v_max_f32_e32 v249, 0xda24260, v249
	v_max_f32_e32 v250, 0xda24260, v250
	v_max_f32_e32 v251, 0xda24260, v251
	v_max_f32_e32 v252, 0xda24260, v252
	v_max_f32_e32 v253, 0xda24260, v253
	v_max_f32_e32 v176, 0xda24260, v176
	v_max_f32_e32 v177, 0xda24260, v177
	v_pk_mul_f32 v[80:81], v[80:81], v[248:249]
	v_pk_mul_f32 v[82:83], v[82:83], v[250:251]
	v_pk_mul_f32 v[76:77], v[76:77], v[252:253]
	v_pk_mul_f32 v[78:79], v[78:79], v[176:177]
	v_cvt_pk_bf16_f32 v240, v80, v81
	v_cvt_pk_bf16_f32 v241, v82, v83
	v_cvt_pk_bf16_f32 v242, v76, v77
	v_cvt_pk_bf16_f32 v243, v78, v79
	global_store_dwordx4 v[154:155], v[240:243], off
	s_waitcnt vmcnt(15)
	v_lshlrev_b32_e32 v248, 16, v244
	v_and_b32_e32 v249, 0xffff0000, v244
	v_lshlrev_b32_e32 v250, 16, v245
	v_and_b32_e32 v251, 0xffff0000, v245
	v_lshlrev_b32_e32 v252, 16, v246
	v_and_b32_e32 v253, 0xffff0000, v246
	v_lshlrev_b32_e32 v176, 16, v247
	v_and_b32_e32 v177, 0xffff0000, v247
	v_max_f32_e32 v248, 0xda24260, v248
	v_max_f32_e32 v249, 0xda24260, v249
	v_max_f32_e32 v250, 0xda24260, v250
	v_max_f32_e32 v251, 0xda24260, v251
	v_max_f32_e32 v252, 0xda24260, v252
	v_max_f32_e32 v253, 0xda24260, v253
	v_max_f32_e32 v176, 0xda24260, v176
	v_max_f32_e32 v177, 0xda24260, v177
	v_pk_mul_f32 v[72:73], v[72:73], v[248:249]
	v_pk_mul_f32 v[74:75], v[74:75], v[250:251]
	v_pk_mul_f32 v[68:69], v[68:69], v[252:253]
	v_pk_mul_f32 v[70:71], v[70:71], v[176:177]
	v_cvt_pk_bf16_f32 v244, v72, v73
	v_cvt_pk_bf16_f32 v245, v74, v75
	v_cvt_pk_bf16_f32 v246, v68, v69
	v_cvt_pk_bf16_f32 v247, v70, v71
	global_store_dwordx4 v[154:155], v[244:247], off offset:256
	s_mov_b64 s[12:13], 0x28000
	v_lshl_add_u64 v[154:155], v[154:155], 0, s[12:13]
	s_mov_b64 s[12:13], 0x8000
	s_waitcnt vmcnt(15)
	v_lshlrev_b32_e32 v248, 16, v198
	v_and_b32_e32 v249, 0xffff0000, v198
	v_lshlrev_b32_e32 v250, 16, v199
	v_and_b32_e32 v251, 0xffff0000, v199
	v_lshlrev_b32_e32 v252, 16, v200
	v_and_b32_e32 v253, 0xffff0000, v200
	v_lshlrev_b32_e32 v176, 16, v201
	v_and_b32_e32 v177, 0xffff0000, v201
	v_max_f32_e32 v248, 0xda24260, v248
	v_max_f32_e32 v249, 0xda24260, v249
	v_max_f32_e32 v250, 0xda24260, v250
	v_max_f32_e32 v251, 0xda24260, v251
	v_max_f32_e32 v252, 0xda24260, v252
	v_max_f32_e32 v253, 0xda24260, v253
	v_max_f32_e32 v176, 0xda24260, v176
	v_max_f32_e32 v177, 0xda24260, v177
	v_pk_mul_f32 v[64:65], v[64:65], v[248:249]
	v_pk_mul_f32 v[66:67], v[66:67], v[250:251]
	v_pk_mul_f32 v[60:61], v[60:61], v[252:253]
	v_pk_mul_f32 v[62:63], v[62:63], v[176:177]
	v_cvt_pk_bf16_f32 v198, v64, v65
	v_cvt_pk_bf16_f32 v199, v66, v67
	v_cvt_pk_bf16_f32 v200, v60, v61
	v_cvt_pk_bf16_f32 v201, v62, v63
	global_store_dwordx4 v[154:155], v[198:201], off
	s_waitcnt vmcnt(15)
	v_lshlrev_b32_e32 v248, 16, v202
	v_and_b32_e32 v249, 0xffff0000, v202
	v_lshlrev_b32_e32 v250, 16, v203
	v_and_b32_e32 v251, 0xffff0000, v203
	v_lshlrev_b32_e32 v252, 16, v204
	v_and_b32_e32 v253, 0xffff0000, v204
	v_lshlrev_b32_e32 v176, 16, v205
	v_and_b32_e32 v177, 0xffff0000, v205
	v_max_f32_e32 v248, 0xda24260, v248
	v_max_f32_e32 v249, 0xda24260, v249
	v_max_f32_e32 v250, 0xda24260, v250
	v_max_f32_e32 v251, 0xda24260, v251
	v_max_f32_e32 v252, 0xda24260, v252
	v_max_f32_e32 v253, 0xda24260, v253
	v_max_f32_e32 v176, 0xda24260, v176
	v_max_f32_e32 v177, 0xda24260, v177
	v_pk_mul_f32 v[56:57], v[56:57], v[248:249]
	v_pk_mul_f32 v[58:59], v[58:59], v[250:251]
	v_pk_mul_f32 v[52:53], v[52:53], v[252:253]
	v_pk_mul_f32 v[54:55], v[54:55], v[176:177]
	v_cvt_pk_bf16_f32 v202, v56, v57
	v_cvt_pk_bf16_f32 v203, v58, v59
	v_cvt_pk_bf16_f32 v204, v52, v53
	v_cvt_pk_bf16_f32 v205, v54, v55
	global_store_dwordx4 v[154:155], v[202:205], off offset:256
	v_lshl_add_u64 v[154:155], v[154:155], 0, s[12:13]
	s_waitcnt vmcnt(15)
	v_lshlrev_b32_e32 v248, 16, v206
	v_and_b32_e32 v249, 0xffff0000, v206
	v_lshlrev_b32_e32 v250, 16, v207
	v_and_b32_e32 v251, 0xffff0000, v207
	v_lshlrev_b32_e32 v252, 16, v208
	v_and_b32_e32 v253, 0xffff0000, v208
	v_lshlrev_b32_e32 v176, 16, v209
	v_and_b32_e32 v177, 0xffff0000, v209
	v_max_f32_e32 v248, 0xda24260, v248
	v_max_f32_e32 v249, 0xda24260, v249
	v_max_f32_e32 v250, 0xda24260, v250
	v_max_f32_e32 v251, 0xda24260, v251
	v_max_f32_e32 v252, 0xda24260, v252
	v_max_f32_e32 v253, 0xda24260, v253
	v_max_f32_e32 v176, 0xda24260, v176
	v_max_f32_e32 v177, 0xda24260, v177
	v_pk_mul_f32 v[48:49], v[48:49], v[248:249]
	v_pk_mul_f32 v[50:51], v[50:51], v[250:251]
	v_pk_mul_f32 v[44:45], v[44:45], v[252:253]
	v_pk_mul_f32 v[46:47], v[46:47], v[176:177]
	v_cvt_pk_bf16_f32 v206, v48, v49
	v_cvt_pk_bf16_f32 v207, v50, v51
	v_cvt_pk_bf16_f32 v208, v44, v45
	v_cvt_pk_bf16_f32 v209, v46, v47
	global_store_dwordx4 v[154:155], v[206:209], off
	s_waitcnt vmcnt(15)
	v_lshlrev_b32_e32 v248, 16, v210
	v_and_b32_e32 v249, 0xffff0000, v210
	v_lshlrev_b32_e32 v250, 16, v211
	v_and_b32_e32 v251, 0xffff0000, v211
	v_lshlrev_b32_e32 v252, 16, v212
	v_and_b32_e32 v253, 0xffff0000, v212
	v_lshlrev_b32_e32 v176, 16, v213
	v_and_b32_e32 v177, 0xffff0000, v213
	v_max_f32_e32 v248, 0xda24260, v248
	v_max_f32_e32 v249, 0xda24260, v249
	v_max_f32_e32 v250, 0xda24260, v250
	v_max_f32_e32 v251, 0xda24260, v251
	v_max_f32_e32 v252, 0xda24260, v252
	v_max_f32_e32 v253, 0xda24260, v253
	v_max_f32_e32 v176, 0xda24260, v176
	v_max_f32_e32 v177, 0xda24260, v177
	v_pk_mul_f32 v[40:41], v[40:41], v[248:249]
	v_pk_mul_f32 v[42:43], v[42:43], v[250:251]
	v_pk_mul_f32 v[36:37], v[36:37], v[252:253]
	v_pk_mul_f32 v[38:39], v[38:39], v[176:177]
	v_cvt_pk_bf16_f32 v210, v40, v41
	v_cvt_pk_bf16_f32 v211, v42, v43
	v_cvt_pk_bf16_f32 v212, v36, v37
	v_cvt_pk_bf16_f32 v213, v38, v39
	global_store_dwordx4 v[154:155], v[210:213], off offset:256
	v_lshl_add_u64 v[154:155], v[154:155], 0, s[12:13]
	s_waitcnt vmcnt(15)
	v_lshlrev_b32_e32 v248, 16, v164
	v_and_b32_e32 v249, 0xffff0000, v164
	v_lshlrev_b32_e32 v250, 16, v165
	v_and_b32_e32 v251, 0xffff0000, v165
	v_lshlrev_b32_e32 v252, 16, v166
	v_and_b32_e32 v253, 0xffff0000, v166
	v_lshlrev_b32_e32 v176, 16, v167
	v_and_b32_e32 v177, 0xffff0000, v167
	v_max_f32_e32 v248, 0xda24260, v248
	v_max_f32_e32 v249, 0xda24260, v249
	v_max_f32_e32 v250, 0xda24260, v250
	v_max_f32_e32 v251, 0xda24260, v251
	v_max_f32_e32 v252, 0xda24260, v252
	v_max_f32_e32 v253, 0xda24260, v253
	v_max_f32_e32 v176, 0xda24260, v176
	v_max_f32_e32 v177, 0xda24260, v177
	v_pk_mul_f32 v[32:33], v[32:33], v[248:249]
	v_pk_mul_f32 v[34:35], v[34:35], v[250:251]
	v_pk_mul_f32 v[28:29], v[28:29], v[252:253]
	v_pk_mul_f32 v[30:31], v[30:31], v[176:177]
	v_cvt_pk_bf16_f32 v164, v32, v33
	v_cvt_pk_bf16_f32 v165, v34, v35
	v_cvt_pk_bf16_f32 v166, v28, v29
	v_cvt_pk_bf16_f32 v167, v30, v31
	global_store_dwordx4 v[154:155], v[164:167], off
	s_waitcnt vmcnt(15)
	v_lshlrev_b32_e32 v248, 16, v168
	v_and_b32_e32 v249, 0xffff0000, v168
	v_lshlrev_b32_e32 v250, 16, v169
	v_and_b32_e32 v251, 0xffff0000, v169
	v_lshlrev_b32_e32 v252, 16, v170
	v_and_b32_e32 v253, 0xffff0000, v170
	v_lshlrev_b32_e32 v176, 16, v171
	v_and_b32_e32 v177, 0xffff0000, v171
	v_max_f32_e32 v248, 0xda24260, v248
	v_max_f32_e32 v249, 0xda24260, v249
	v_max_f32_e32 v250, 0xda24260, v250
	v_max_f32_e32 v251, 0xda24260, v251
	v_max_f32_e32 v252, 0xda24260, v252
	v_max_f32_e32 v253, 0xda24260, v253
	v_max_f32_e32 v176, 0xda24260, v176
	v_max_f32_e32 v177, 0xda24260, v177
	v_pk_mul_f32 v[24:25], v[24:25], v[248:249]
	v_pk_mul_f32 v[26:27], v[26:27], v[250:251]
	v_pk_mul_f32 v[20:21], v[20:21], v[252:253]
	v_pk_mul_f32 v[22:23], v[22:23], v[176:177]
	v_cvt_pk_bf16_f32 v168, v24, v25
	v_cvt_pk_bf16_f32 v169, v26, v27
	v_cvt_pk_bf16_f32 v170, v20, v21
	v_cvt_pk_bf16_f32 v171, v22, v23
	global_store_dwordx4 v[154:155], v[168:171], off offset:256
	v_lshl_add_u64 v[154:155], v[154:155], 0, s[12:13]
	s_waitcnt vmcnt(15)
	v_lshlrev_b32_e32 v248, 16, v172
	v_and_b32_e32 v249, 0xffff0000, v172
	v_lshlrev_b32_e32 v250, 16, v173
	v_and_b32_e32 v251, 0xffff0000, v173
	v_lshlrev_b32_e32 v252, 16, v174
	v_and_b32_e32 v253, 0xffff0000, v174
	v_lshlrev_b32_e32 v176, 16, v175
	v_and_b32_e32 v177, 0xffff0000, v175
	v_max_f32_e32 v248, 0xda24260, v248
	v_max_f32_e32 v249, 0xda24260, v249
	v_max_f32_e32 v250, 0xda24260, v250
	v_max_f32_e32 v251, 0xda24260, v251
	v_max_f32_e32 v252, 0xda24260, v252
	v_max_f32_e32 v253, 0xda24260, v253
	v_max_f32_e32 v176, 0xda24260, v176
	v_max_f32_e32 v177, 0xda24260, v177
	v_pk_mul_f32 v[16:17], v[16:17], v[248:249]
	v_pk_mul_f32 v[18:19], v[18:19], v[250:251]
	v_pk_mul_f32 v[12:13], v[12:13], v[252:253]
	v_pk_mul_f32 v[14:15], v[14:15], v[176:177]
	v_cvt_pk_bf16_f32 v172, v16, v17
	v_cvt_pk_bf16_f32 v173, v18, v19
	v_cvt_pk_bf16_f32 v174, v12, v13
	v_cvt_pk_bf16_f32 v175, v14, v15
	global_store_dwordx4 v[154:155], v[172:175], off
	s_waitcnt vmcnt(15)
	v_lshlrev_b32_e32 v248, 16, v132
	v_and_b32_e32 v249, 0xffff0000, v132
	v_lshlrev_b32_e32 v250, 16, v133
	v_and_b32_e32 v251, 0xffff0000, v133
	v_lshlrev_b32_e32 v252, 16, v134
	v_and_b32_e32 v253, 0xffff0000, v134
	v_lshlrev_b32_e32 v176, 16, v135
	v_and_b32_e32 v177, 0xffff0000, v135
	v_max_f32_e32 v248, 0xda24260, v248
	v_max_f32_e32 v249, 0xda24260, v249
	v_max_f32_e32 v250, 0xda24260, v250
	v_max_f32_e32 v251, 0xda24260, v251
	v_max_f32_e32 v252, 0xda24260, v252
	v_max_f32_e32 v253, 0xda24260, v253
	v_max_f32_e32 v176, 0xda24260, v176
	v_max_f32_e32 v177, 0xda24260, v177
	v_pk_mul_f32 v[8:9], v[8:9], v[248:249]
	v_pk_mul_f32 v[10:11], v[10:11], v[250:251]
	v_pk_mul_f32 v[4:5], v[4:5], v[252:253]
	v_pk_mul_f32 v[6:7], v[6:7], v[176:177]
	v_cvt_pk_bf16_f32 v132, v8, v9
	v_cvt_pk_bf16_f32 v133, v10, v11
	v_cvt_pk_bf16_f32 v134, v4, v5
	v_cvt_pk_bf16_f32 v135, v6, v7
	global_store_dwordx4 v[154:155], v[132:135], off offset:256
	s_mov_b64 s[10:11], -1
	s_andn2_b64 vcc, exec, s[40:41]
	s_cbranch_vccnz .LBB0_538
	s_andn2_b64 vcc, exec, s[2:3]
	s_cbranch_vccnz .LBB0_537
	s_barrier
	s_branch .LBB0_537

.LBB0_643:
	v_and_b32_e32 v156, 64, v215
	v_xor_b32_e32 v147, 16, v215
	v_add_u32_e32 v156, 64, v156
	v_cmp_lt_i32_e32 vcc, v147, v156
	s_cmpk_lt_i32 s10, 0x80
	v_lshl_add_u32 v146, s10, 8, v150
	v_cndmask_b32_e32 v147, v215, v147, vcc
	v_lshlrev_b32_e32 v157, 2, v147
	v_xor_b32_e32 v147, 32, v215
	v_cmp_lt_i32_e32 vcc, v147, v156
	v_lshl_or_b32 v144, s2, 8, v152
	s_cselect_b32 s10, s45, s62
	s_cselect_b32 s11, s44, s61
	v_cndmask_b32_e32 v147, v215, v147, vcc
	v_mov_b32_e32 v148, s11
	v_mov_b32_e32 v149, s10
	v_ashrrev_i32_e32 v145, 31, v144
	v_lshlrev_b32_e32 v156, 2, v147
	v_ashrrev_i32_e32 v147, 31, v146
	v_lshl_add_u64 v[148:149], v[144:145], 2, v[148:149]
	v_lshlrev_b64 v[158:159], 12, v[146:147]
	v_lshl_add_u64 v[148:149], v[148:149], 0, v[158:159]
	s_lshl_b32 s10, s2, 2
	s_ashr_i32 s11, s10, 31
	s_lshl_b32 s2, s23, 2
	v_lshlrev_b64 v[158:159], 6, v[146:147]
	v_lshlrev_b64 v[146:147], 11, v[146:147]
	v_lshl_add_u64 v[158:159], s[0:1], 0, v[158:159]
	v_lshl_add_u64 v[146:147], s[96:97], 0, v[146:147]
	v_lshl_add_u64 v[158:159], s[10:11], 2, v[158:159]
	v_lshl_add_u64 v[144:145], v[144:145], 1, v[146:147]
	v_lshl_add_u64 v[146:147], v[158:159], 0, s[2:3]
	s_mov_b64 s[10:11], 0x10000
	s_mov_b64 s[12:13], 0x8000
	global_load_dwordx4 v[160:163], v[148:149], off nt
	global_load_dwordx4 v[164:167], v[148:149], off offset:16 nt
	global_load_dwordx4 v[168:171], v[148:149], off offset:512 nt
	global_load_dwordx4 v[172:175], v[148:149], off offset:528 nt
	v_lshl_add_u64 v[148:149], v[148:149], 0, s[10:11]
	global_load_dwordx4 v[176:179], v[148:149], off nt
	global_load_dwordx4 v[180:183], v[148:149], off offset:16 nt
	global_load_dwordx4 v[184:187], v[148:149], off offset:512 nt
	global_load_dwordx4 v[188:191], v[148:149], off offset:528 nt
	v_lshl_add_u64 v[148:149], v[148:149], 0, s[10:11]
	global_load_dwordx4 v[192:195], v[148:149], off nt
	global_load_dwordx4 v[196:199], v[148:149], off offset:16 nt
	global_load_dwordx4 v[200:203], v[148:149], off offset:512 nt
	global_load_dwordx4 v[204:207], v[148:149], off offset:528 nt
	v_lshl_add_u64 v[148:149], v[148:149], 0, s[10:11]
	global_load_dwordx4 v[208:211], v[148:149], off nt
	global_load_dwordx4 v[216:219], v[148:149], off offset:16 nt
	s_waitcnt vmcnt(12)
	v_pk_add_f32 v[124:125], v[124:125], v[160:161]
	v_pk_add_f32 v[126:127], v[126:127], v[162:163]
	v_pk_add_f32 v[120:121], v[120:121], v[164:165]
	v_pk_add_f32 v[122:123], v[122:123], v[166:167]
	global_load_dwordx4 v[160:163], v[148:149], off offset:512 nt
	global_load_dwordx4 v[164:167], v[148:149], off offset:528 nt
	s_mov_b64 s[10:11], 0x50000
	v_lshl_add_u64 v[148:149], v[148:149], 0, s[10:11]
	s_mov_b64 s[10:11], 0x10000
	v_mul_f32_e32 v158, v125, v125
	v_mul_f32_e32 v159, v127, v127
	v_fmac_f32_e32 v158, v124, v124
	v_fmac_f32_e32 v159, v126, v126
	v_add_f32_e32 v158, v158, v159
	v_mul_f32_e32 v159, v121, v121
	v_fmac_f32_e32 v159, v120, v120
	v_add_f32_e32 v158, v158, v159
	v_mul_f32_e32 v159, v123, v123
	v_fmac_f32_e32 v159, v122, v122
	v_add_f32_e32 v158, v159, v158
	v_cvt_pk_bf16_f32 v124, v124, v125
	v_cvt_pk_bf16_f32 v125, v126, v127
	v_cvt_pk_bf16_f32 v126, v120, v121
	v_cvt_pk_bf16_f32 v127, v122, v123
	global_store_dwordx4 v[144:145], v[124:127], off
	v_mov_b32_e32 v120, v158
	s_waitcnt vmcnt(13)
	v_pk_add_f32 v[116:117], v[116:117], v[168:169]
	v_pk_add_f32 v[118:119], v[118:119], v[170:171]
	v_pk_add_f32 v[112:113], v[112:113], v[172:173]
	v_pk_add_f32 v[114:115], v[114:115], v[174:175]
	global_load_dwordx4 v[168:171], v[148:149], off nt
	global_load_dwordx4 v[172:175], v[148:149], off offset:16 nt
	v_mul_f32_e32 v158, v117, v117
	v_mul_f32_e32 v159, v119, v119
	v_fmac_f32_e32 v158, v116, v116
	v_fmac_f32_e32 v159, v118, v118
	v_add_f32_e32 v158, v158, v159
	v_mul_f32_e32 v159, v113, v113
	v_fmac_f32_e32 v159, v112, v112
	v_add_f32_e32 v158, v158, v159
	v_mul_f32_e32 v159, v115, v115
	v_fmac_f32_e32 v159, v114, v114
	v_add_f32_e32 v158, v159, v158
	v_cvt_pk_bf16_f32 v116, v116, v117
	v_cvt_pk_bf16_f32 v117, v118, v119
	v_cvt_pk_bf16_f32 v118, v112, v113
	v_cvt_pk_bf16_f32 v119, v114, v115
	global_store_dwordx4 v[144:145], v[116:119], off offset:256
	v_add_f32_e32 v112, v120, v158
	v_lshl_add_u64 v[144:145], v[144:145], 0, s[12:13]
	s_waitcnt vmcnt(14)
	v_pk_add_f32 v[108:109], v[108:109], v[176:177]
	v_pk_add_f32 v[110:111], v[110:111], v[178:179]
	v_pk_add_f32 v[104:105], v[104:105], v[180:181]
	v_pk_add_f32 v[106:107], v[106:107], v[182:183]
	global_load_dwordx4 v[176:179], v[148:149], off offset:512 nt
	global_load_dwordx4 v[180:183], v[148:149], off offset:528 nt
	v_lshl_add_u64 v[148:149], v[148:149], 0, s[10:11]
	v_mul_f32_e32 v158, v109, v109
	v_mul_f32_e32 v159, v111, v111
	v_fmac_f32_e32 v158, v108, v108
	v_fmac_f32_e32 v159, v110, v110
	v_add_f32_e32 v158, v158, v159
	v_mul_f32_e32 v159, v105, v105
	v_fmac_f32_e32 v159, v104, v104
	v_add_f32_e32 v158, v158, v159
	v_mul_f32_e32 v159, v107, v107
	v_fmac_f32_e32 v159, v106, v106
	v_add_f32_e32 v158, v159, v158
	v_cvt_pk_bf16_f32 v108, v108, v109
	v_cvt_pk_bf16_f32 v109, v110, v111
	v_cvt_pk_bf16_f32 v110, v104, v105
	v_cvt_pk_bf16_f32 v111, v106, v107
	global_store_dwordx4 v[144:145], v[108:111], off
	v_mov_b32_e32 v104, v158
	s_waitcnt vmcnt(15)
	v_pk_add_f32 v[100:101], v[100:101], v[184:185]
	v_pk_add_f32 v[102:103], v[102:103], v[186:187]
	v_pk_add_f32 v[96:97], v[96:97], v[188:189]
	v_pk_add_f32 v[98:99], v[98:99], v[190:191]
	global_load_dwordx4 v[184:187], v[148:149], off nt
	global_load_dwordx4 v[188:191], v[148:149], off offset:16 nt
	v_mul_f32_e32 v158, v101, v101
	v_mul_f32_e32 v159, v103, v103
	v_fmac_f32_e32 v158, v100, v100
	v_fmac_f32_e32 v159, v102, v102
	v_add_f32_e32 v158, v158, v159
	v_mul_f32_e32 v159, v97, v97
	v_fmac_f32_e32 v159, v96, v96
	v_add_f32_e32 v158, v158, v159
	v_mul_f32_e32 v159, v99, v99
	v_fmac_f32_e32 v159, v98, v98
	v_add_f32_e32 v158, v159, v158
	v_cvt_pk_bf16_f32 v100, v100, v101
	v_cvt_pk_bf16_f32 v101, v102, v103
	v_cvt_pk_bf16_f32 v102, v96, v97
	v_cvt_pk_bf16_f32 v103, v98, v99
	global_store_dwordx4 v[144:145], v[100:103], off offset:256
	v_add_f32_e32 v96, v104, v158
	v_lshl_add_u64 v[144:145], v[144:145], 0, s[12:13]
	s_waitcnt vmcnt(16)
	v_pk_add_f32 v[92:93], v[92:93], v[192:193]
	v_pk_add_f32 v[94:95], v[94:95], v[194:195]
	v_pk_add_f32 v[88:89], v[88:89], v[196:197]
	v_pk_add_f32 v[90:91], v[90:91], v[198:199]
	global_load_dwordx4 v[192:195], v[148:149], off offset:512 nt
	global_load_dwordx4 v[196:199], v[148:149], off offset:528 nt
	v_lshl_add_u64 v[148:149], v[148:149], 0, s[10:11]
	v_mul_f32_e32 v158, v93, v93
	v_mul_f32_e32 v159, v95, v95
	v_fmac_f32_e32 v158, v92, v92
	v_fmac_f32_e32 v159, v94, v94
	v_add_f32_e32 v158, v158, v159
	v_mul_f32_e32 v159, v89, v89
	v_fmac_f32_e32 v159, v88, v88
	v_add_f32_e32 v158, v158, v159
	v_mul_f32_e32 v159, v91, v91
	v_fmac_f32_e32 v159, v90, v90
	v_add_f32_e32 v158, v159, v158
	v_cvt_pk_bf16_f32 v92, v92, v93
	v_cvt_pk_bf16_f32 v93, v94, v95
	v_cvt_pk_bf16_f32 v94, v88, v89
	v_cvt_pk_bf16_f32 v95, v90, v91
	global_store_dwordx4 v[144:145], v[92:95], off
	v_mov_b32_e32 v88, v158
	s_waitcnt vmcnt(17)
	v_pk_add_f32 v[84:85], v[84:85], v[200:201]
	v_pk_add_f32 v[86:87], v[86:87], v[202:203]
	v_pk_add_f32 v[80:81], v[80:81], v[204:205]
	v_pk_add_f32 v[82:83], v[82:83], v[206:207]
	global_load_dwordx4 v[200:203], v[148:149], off nt
	global_load_dwordx4 v[204:207], v[148:149], off offset:16 nt
	v_mul_f32_e32 v158, v85, v85
	v_mul_f32_e32 v159, v87, v87
	v_fmac_f32_e32 v158, v84, v84
	v_fmac_f32_e32 v159, v86, v86
	v_add_f32_e32 v158, v158, v159
	v_mul_f32_e32 v159, v81, v81
	v_fmac_f32_e32 v159, v80, v80
	v_add_f32_e32 v158, v158, v159
	v_mul_f32_e32 v159, v83, v83
	v_fmac_f32_e32 v159, v82, v82
	v_add_f32_e32 v158, v159, v158
	v_cvt_pk_bf16_f32 v84, v84, v85
	v_cvt_pk_bf16_f32 v85, v86, v87
	v_cvt_pk_bf16_f32 v86, v80, v81
	v_cvt_pk_bf16_f32 v87, v82, v83
	global_store_dwordx4 v[144:145], v[84:87], off offset:256
	v_add_f32_e32 v80, v88, v158
	v_lshl_add_u64 v[144:145], v[144:145], 0, s[12:13]
	s_waitcnt vmcnt(18)
	v_pk_add_f32 v[76:77], v[76:77], v[208:209]
	v_pk_add_f32 v[78:79], v[78:79], v[210:211]
	v_pk_add_f32 v[72:73], v[72:73], v[216:217]
	v_pk_add_f32 v[74:75], v[74:75], v[218:219]
	global_load_dwordx4 v[208:211], v[148:149], off offset:512 nt
	global_load_dwordx4 v[216:219], v[148:149], off offset:528 nt
	v_lshl_add_u64 v[148:149], v[148:149], 0, s[10:11]
	v_mul_f32_e32 v158, v77, v77
	v_mul_f32_e32 v159, v79, v79
	v_fmac_f32_e32 v158, v76, v76
	v_fmac_f32_e32 v159, v78, v78
	v_add_f32_e32 v158, v158, v159
	v_mul_f32_e32 v159, v73, v73
	v_fmac_f32_e32 v159, v72, v72
	v_add_f32_e32 v158, v158, v159
	v_mul_f32_e32 v159, v75, v75
	v_fmac_f32_e32 v159, v74, v74
	v_add_f32_e32 v158, v159, v158
	v_cvt_pk_bf16_f32 v76, v76, v77
	v_cvt_pk_bf16_f32 v77, v78, v79
	v_cvt_pk_bf16_f32 v78, v72, v73
	v_cvt_pk_bf16_f32 v79, v74, v75
	global_store_dwordx4 v[144:145], v[76:79], off
	v_mov_b32_e32 v72, v158
	s_waitcnt vmcnt(19)
	v_pk_add_f32 v[68:69], v[68:69], v[160:161]
	v_pk_add_f32 v[70:71], v[70:71], v[162:163]
	v_pk_add_f32 v[64:65], v[64:65], v[164:165]
	v_pk_add_f32 v[66:67], v[66:67], v[166:167]
	global_load_dwordx4 v[160:163], v[148:149], off nt
	global_load_dwordx4 v[164:167], v[148:149], off offset:16 nt
	v_mul_f32_e32 v158, v69, v69
	v_mul_f32_e32 v159, v71, v71
	v_fmac_f32_e32 v158, v68, v68
	v_fmac_f32_e32 v159, v70, v70
	v_add_f32_e32 v158, v158, v159
	v_mul_f32_e32 v159, v65, v65
	v_fmac_f32_e32 v159, v64, v64
	v_add_f32_e32 v158, v158, v159
	v_mul_f32_e32 v159, v67, v67
	v_fmac_f32_e32 v159, v66, v66
	v_add_f32_e32 v158, v159, v158
	v_cvt_pk_bf16_f32 v68, v68, v69
	v_cvt_pk_bf16_f32 v69, v70, v71
	v_cvt_pk_bf16_f32 v70, v64, v65
	v_cvt_pk_bf16_f32 v71, v66, v67
	global_store_dwordx4 v[144:145], v[68:71], off offset:256
	v_add_f32_e32 v64, v72, v158
	s_mov_b64 s[12:13], 0x28000
	v_lshl_add_u64 v[144:145], v[144:145], 0, s[12:13]
	s_mov_b64 s[12:13], 0x8000
	s_waitcnt vmcnt(19)
	v_pk_add_f32 v[60:61], v[60:61], v[168:169]
	v_pk_add_f32 v[62:63], v[62:63], v[170:171]
	v_pk_add_f32 v[56:57], v[56:57], v[172:173]
	v_pk_add_f32 v[58:59], v[58:59], v[174:175]
	global_load_dwordx4 v[168:171], v[148:149], off offset:512 nt
	global_load_dwordx4 v[172:175], v[148:149], off offset:528 nt
	v_mul_f32_e32 v158, v61, v61
	v_mul_f32_e32 v159, v63, v63
	v_fmac_f32_e32 v158, v60, v60
	v_fmac_f32_e32 v159, v62, v62
	v_add_f32_e32 v158, v158, v159
	v_mul_f32_e32 v159, v57, v57
	v_fmac_f32_e32 v159, v56, v56
	v_add_f32_e32 v158, v158, v159
	v_mul_f32_e32 v159, v59, v59
	v_fmac_f32_e32 v159, v58, v58
	v_add_f32_e32 v158, v159, v158
	v_cvt_pk_bf16_f32 v60, v60, v61
	v_cvt_pk_bf16_f32 v61, v62, v63
	v_cvt_pk_bf16_f32 v62, v56, v57
	v_cvt_pk_bf16_f32 v63, v58, v59
	global_store_dwordx4 v[144:145], v[60:63], off
	v_mov_b32_e32 v56, v158
	s_waitcnt vmcnt(19)
	v_pk_add_f32 v[52:53], v[52:53], v[176:177]
	v_pk_add_f32 v[54:55], v[54:55], v[178:179]
	v_pk_add_f32 v[48:49], v[48:49], v[180:181]
	v_pk_add_f32 v[50:51], v[50:51], v[182:183]
	v_mul_f32_e32 v158, v53, v53
	v_mul_f32_e32 v159, v55, v55
	v_fmac_f32_e32 v158, v52, v52
	v_fmac_f32_e32 v159, v54, v54
	v_add_f32_e32 v158, v158, v159
	v_mul_f32_e32 v159, v49, v49
	v_fmac_f32_e32 v159, v48, v48
	v_add_f32_e32 v158, v158, v159
	v_mul_f32_e32 v159, v51, v51
	v_fmac_f32_e32 v159, v50, v50
	v_add_f32_e32 v158, v159, v158
	v_cvt_pk_bf16_f32 v52, v52, v53
	v_cvt_pk_bf16_f32 v53, v54, v55
	v_cvt_pk_bf16_f32 v54, v48, v49
	v_cvt_pk_bf16_f32 v55, v50, v51
	global_store_dwordx4 v[144:145], v[52:55], off offset:256
	v_add_f32_e32 v48, v56, v158
	v_lshl_add_u64 v[144:145], v[144:145], 0, s[12:13]
	s_waitcnt vmcnt(17)
	v_pk_add_f32 v[44:45], v[44:45], v[184:185]
	v_pk_add_f32 v[46:47], v[46:47], v[186:187]
	v_pk_add_f32 v[40:41], v[40:41], v[188:189]
	v_pk_add_f32 v[42:43], v[42:43], v[190:191]
	v_mul_f32_e32 v158, v45, v45
	v_mul_f32_e32 v159, v47, v47
	v_fmac_f32_e32 v158, v44, v44
	v_fmac_f32_e32 v159, v46, v46
	v_add_f32_e32 v158, v158, v159
	v_mul_f32_e32 v159, v41, v41
	v_fmac_f32_e32 v159, v40, v40
	v_add_f32_e32 v158, v158, v159
	v_mul_f32_e32 v159, v43, v43
	v_fmac_f32_e32 v159, v42, v42
	v_add_f32_e32 v158, v159, v158
	v_cvt_pk_bf16_f32 v44, v44, v45
	v_cvt_pk_bf16_f32 v45, v46, v47
	v_cvt_pk_bf16_f32 v46, v40, v41
	v_cvt_pk_bf16_f32 v47, v42, v43
	global_store_dwordx4 v[144:145], v[44:47], off
	v_mov_b32_e32 v40, v158
	s_waitcnt vmcnt(15)
	v_pk_add_f32 v[36:37], v[36:37], v[192:193]
	v_pk_add_f32 v[38:39], v[38:39], v[194:195]
	v_pk_add_f32 v[32:33], v[32:33], v[196:197]
	v_pk_add_f32 v[34:35], v[34:35], v[198:199]
	v_mul_f32_e32 v158, v37, v37
	v_mul_f32_e32 v159, v39, v39
	v_fmac_f32_e32 v158, v36, v36
	v_fmac_f32_e32 v159, v38, v38
	v_add_f32_e32 v158, v158, v159
	v_mul_f32_e32 v159, v33, v33
	v_fmac_f32_e32 v159, v32, v32
	v_add_f32_e32 v158, v158, v159
	v_mul_f32_e32 v159, v35, v35
	v_fmac_f32_e32 v159, v34, v34
	v_add_f32_e32 v158, v159, v158
	v_cvt_pk_bf16_f32 v36, v36, v37
	v_cvt_pk_bf16_f32 v37, v38, v39
	v_cvt_pk_bf16_f32 v38, v32, v33
	v_cvt_pk_bf16_f32 v39, v34, v35
	global_store_dwordx4 v[144:145], v[36:39], off offset:256
	v_add_f32_e32 v32, v40, v158
	v_lshl_add_u64 v[144:145], v[144:145], 0, s[12:13]
	s_waitcnt vmcnt(13)
	v_pk_add_f32 v[28:29], v[28:29], v[200:201]
	v_pk_add_f32 v[30:31], v[30:31], v[202:203]
	v_pk_add_f32 v[24:25], v[24:25], v[204:205]
	v_pk_add_f32 v[26:27], v[26:27], v[206:207]
	v_mul_f32_e32 v158, v29, v29
	v_mul_f32_e32 v159, v31, v31
	v_fmac_f32_e32 v158, v28, v28
	v_fmac_f32_e32 v159, v30, v30
	v_add_f32_e32 v158, v158, v159
	v_mul_f32_e32 v159, v25, v25
	v_fmac_f32_e32 v159, v24, v24
	v_add_f32_e32 v158, v158, v159
	v_mul_f32_e32 v159, v27, v27
	v_fmac_f32_e32 v159, v26, v26
	v_add_f32_e32 v158, v159, v158
	v_cvt_pk_bf16_f32 v28, v28, v29
	v_cvt_pk_bf16_f32 v29, v30, v31
	v_cvt_pk_bf16_f32 v30, v24, v25
	v_cvt_pk_bf16_f32 v31, v26, v27
	global_store_dwordx4 v[144:145], v[28:31], off
	v_mov_b32_e32 v24, v158
	s_waitcnt vmcnt(11)
	v_pk_add_f32 v[20:21], v[20:21], v[208:209]
	v_pk_add_f32 v[22:23], v[22:23], v[210:211]
	v_pk_add_f32 v[16:17], v[16:17], v[216:217]
	v_pk_add_f32 v[18:19], v[18:19], v[218:219]
	v_mul_f32_e32 v158, v21, v21
	v_mul_f32_e32 v159, v23, v23
	v_fmac_f32_e32 v158, v20, v20
	v_fmac_f32_e32 v159, v22, v22
	v_add_f32_e32 v158, v158, v159
	v_mul_f32_e32 v159, v17, v17
	v_fmac_f32_e32 v159, v16, v16
	v_add_f32_e32 v158, v158, v159
	v_mul_f32_e32 v159, v19, v19
	v_fmac_f32_e32 v159, v18, v18
	v_add_f32_e32 v158, v159, v158
	v_cvt_pk_bf16_f32 v20, v20, v21
	v_cvt_pk_bf16_f32 v21, v22, v23
	v_cvt_pk_bf16_f32 v22, v16, v17
	v_cvt_pk_bf16_f32 v23, v18, v19
	global_store_dwordx4 v[144:145], v[20:23], off offset:256
	v_add_f32_e32 v16, v24, v158
	v_lshl_add_u64 v[144:145], v[144:145], 0, s[12:13]
	s_waitcnt vmcnt(9)
	v_pk_add_f32 v[12:13], v[12:13], v[160:161]
	v_pk_add_f32 v[14:15], v[14:15], v[162:163]
	v_pk_add_f32 v[8:9], v[8:9], v[164:165]
	v_pk_add_f32 v[10:11], v[10:11], v[166:167]
	v_mul_f32_e32 v158, v13, v13
	v_mul_f32_e32 v159, v15, v15
	v_fmac_f32_e32 v158, v12, v12
	v_fmac_f32_e32 v159, v14, v14
	v_add_f32_e32 v158, v158, v159
	v_mul_f32_e32 v159, v9, v9
	v_fmac_f32_e32 v159, v8, v8
	v_add_f32_e32 v158, v158, v159
	v_mul_f32_e32 v159, v11, v11
	v_fmac_f32_e32 v159, v10, v10
	v_add_f32_e32 v158, v159, v158
	v_cvt_pk_bf16_f32 v12, v12, v13
	v_cvt_pk_bf16_f32 v13, v14, v15
	v_cvt_pk_bf16_f32 v14, v8, v9
	v_cvt_pk_bf16_f32 v15, v10, v11
	global_store_dwordx4 v[144:145], v[12:15], off
	v_mov_b32_e32 v8, v158
	s_waitcnt vmcnt(7)
	v_pk_add_f32 v[4:5], v[4:5], v[168:169]
	v_pk_add_f32 v[6:7], v[6:7], v[170:171]
	v_pk_add_f32 v[0:1], v[0:1], v[172:173]
	v_pk_add_f32 v[2:3], v[2:3], v[174:175]
	v_mul_f32_e32 v158, v5, v5
	v_mul_f32_e32 v159, v7, v7
	v_fmac_f32_e32 v158, v4, v4
	v_fmac_f32_e32 v159, v6, v6
	v_add_f32_e32 v158, v158, v159
	v_mul_f32_e32 v159, v1, v1
	v_fmac_f32_e32 v159, v0, v0
	v_add_f32_e32 v158, v158, v159
	v_mul_f32_e32 v159, v3, v3
	v_fmac_f32_e32 v159, v2, v2
	v_add_f32_e32 v158, v159, v158
	v_cvt_pk_bf16_f32 v4, v4, v5
	v_cvt_pk_bf16_f32 v5, v6, v7
	v_cvt_pk_bf16_f32 v6, v0, v1
	v_cvt_pk_bf16_f32 v7, v2, v3
	global_store_dwordx4 v[144:145], v[4:7], off offset:256
	v_add_f32_e32 v0, v8, v158
	s_mov_b64 s[10:11], 0x2000
	v_lshl_add_u64 v[148:149], v[146:147], 0, s[10:11]
	ds_bpermute_b32 v113, v157, v112
	ds_bpermute_b32 v97, v157, v96
	ds_bpermute_b32 v81, v157, v80
	ds_bpermute_b32 v65, v157, v64
	ds_bpermute_b32 v49, v157, v48
	ds_bpermute_b32 v33, v157, v32
	ds_bpermute_b32 v17, v157, v16
	ds_bpermute_b32 v1, v157, v0
	s_waitcnt lgkmcnt(7)
	v_add_f32_e32 v112, v112, v113
	s_waitcnt lgkmcnt(6)
	v_add_f32_e32 v96, v96, v97
	s_waitcnt lgkmcnt(5)
	v_add_f32_e32 v80, v80, v81
	s_waitcnt lgkmcnt(4)
	v_add_f32_e32 v64, v64, v65
	s_waitcnt lgkmcnt(3)
	v_add_f32_e32 v48, v48, v49
	s_waitcnt lgkmcnt(2)
	v_add_f32_e32 v32, v32, v33
	s_waitcnt lgkmcnt(1)
	v_add_f32_e32 v16, v16, v17
	s_waitcnt lgkmcnt(0)
	v_add_f32_e32 v0, v0, v1
	ds_bpermute_b32 v113, v156, v112
	ds_bpermute_b32 v97, v156, v96
	ds_bpermute_b32 v81, v156, v80
	ds_bpermute_b32 v65, v156, v64
	ds_bpermute_b32 v49, v156, v48
	ds_bpermute_b32 v33, v156, v32
	ds_bpermute_b32 v17, v156, v16
	ds_bpermute_b32 v1, v156, v0
	s_waitcnt lgkmcnt(7)
	v_add_f32_e32 v112, v112, v113
	s_waitcnt lgkmcnt(6)
	v_add_f32_e32 v96, v96, v97
	s_waitcnt lgkmcnt(5)
	v_add_f32_e32 v80, v80, v81
	s_waitcnt lgkmcnt(4)
	v_add_f32_e32 v64, v64, v65
	s_waitcnt lgkmcnt(3)
	v_add_f32_e32 v48, v48, v49
	s_waitcnt lgkmcnt(2)
	v_add_f32_e32 v32, v32, v33
	s_waitcnt lgkmcnt(1)
	v_add_f32_e32 v16, v16, v17
	s_waitcnt lgkmcnt(0)
	v_add_f32_e32 v0, v0, v1
	s_and_saveexec_b64 s[12:13], s[40:41]
	global_store_dword v[146:147], v112, off
	global_store_dword v[146:147], v96, off offset:1024
	global_store_dword v[146:147], v80, off offset:2048
	global_store_dword v[146:147], v64, off offset:3072
	global_store_dword v[148:149], v48, off
	global_store_dword v[148:149], v32, off offset:1024
	global_store_dword v[148:149], v16, off offset:2048
	global_store_dword v[148:149], v0, off offset:3072
	s_or_b64 exec, exec, s[12:13]
	s_andn2_b64 vcc, exec, s[42:43]
	s_mov_b64 s[10:11], -1
	s_cbranch_vccnz .LBB0_632
	s_andn2_b64 vcc, exec, s[4:5]
	s_cbranch_vccnz .LBB0_631
	s_barrier
	s_branch .LBB0_631
